# K-loops: the last five LDS-DMA loads per iteration in scalar-base form (eight v_lshl_add_u64 per iteration removed)
# baseline (speedup 1.0000x reference)
; #define PG8_STAGE(bufoff, gbase, voff) do { _Pragma("unroll") for (int _i = 0; _i < 2; ++_i) \
;         __builtin_amdgcn_global_load_lds((const unsigned*)((const char*)(gbase) + (voff)[_i]), (PG8_LAS unsigned*)(lds + (bufoff) + ldsw + _i * 8192), 16, 0, 0); } while (0)
; #define PG8_LDA(dst, b, h) do { _Pragma("unroll") for (int m = 0; m < 4; ++m) _Pragma("unroll") for (int k = 0; k < 2; ++k) dst[m][k] = *(const PG8_LAS bf16x8*)(lds + PG8_SA(b, h) + aoff + m * 2048 + k * 1024); } while (0)
; #define PG8_LDB(dst, b, h) do { _Pragma("unroll") for (int n = 0; n < 2; ++n) _Pragma("unroll") for (int k = 0; k < 2; ++k) dst[n][k] = *(const PG8_LAS bf16x8*)(lds + PG8_SB(b, h) + boff + n * 2048 + k * 1024); } while (0)
; #define PG8_SCHED __builtin_amdgcn_sched_barrier(0)
; template <class Epi, class Sched, bool ALIGN_EPI = false, bool SP2 = false>
; __device__ __forceinline__ void gemm_phase(PG8_LAS unsigned char* lds, const Gemm g, const Sched& S, const Epi& E) {
;     ...
;         const bool has_next = S.next(ui + 1, nxt);
;         const char* nA = has_next ? (const char*)g.A + (size_t)nxt.pm * tstep : cA; const char* nB = has_next ? (const char*)g.Bt + (size_t)nxt.pn * tstep : cB;
;         for (int t = 0; t < nt; t += 2) {
;             const bool last = (t == nt - 2);
;             const char* a1 = cA + (size_t)(t + 1) * kstep;
;             const char* a2 = last ? nA : cA + (size_t)(t + 2) * kstep; const char* b2 = last ? nB : cB + (size_t)(t + 2) * kstep;
;             const char* a3 = a2 + kstep; const char* b3 = b2 + kstep;
;             if (last && has_next) S.a_ready(nxt);
;             if constexpr (SP2) {
;             PG8_LDB(B0, 0, 0); PG8_LDB(B1, 0, 1); PG8_SCHED; PG8_LDA(At, 0, 0); PG8_STAGE(PG8_SA(1, 1), a1 + hstep, voffA);
.LBB0_109:
	s_ashr_i32 s75, s74, 31
	s_lshl_b64 s[60:61], s[74:75], 19
	s_add_u32 s76, s40, s60
	s_addc_u32 s77, s41, s61
	s_and_b64 s[60:61], s[4:5], exec
	s_cselect_b32 s1, s77, s7
	s_cselect_b32 s33, s76, s6
	s_ashr_i32 s73, s72, 31
	s_lshl_b64 s[60:61], s[72:73], 19
	s_add_u32 s78, s20, s60
	s_addc_u32 s79, s21, s61
	s_and_b64 s[60:61], s[4:5], exec
	s_cselect_b32 s60, s79, s9
	s_cselect_b32 s61, s78, s8
	s_add_u32 s6, s6, 0x40080
	s_addc_u32 s7, s7, 0
	s_add_u32 s73, s8, 0x100
	s_addc_u32 s75, s9, 0
	s_mov_b32 s84, -2
	ds_read_b128 v[146:149], v160
	ds_read_b128 v[150:153], v160 offset:1024
	ds_read_b128 v[154:157], v160 offset:2048
	ds_read_b128 v[166:169], v160 offset:3072
	ds_read_b128 v[170:173], v161
	ds_read_b128 v[174:177], v161 offset:1024
	ds_read_b128 v[178:181], v161 offset:2048
	ds_read_b128 v[182:185], v161 offset:3072
	s_add_u32 s8, s6, 0xfffc0080
	s_addc_u32 s9, s7, -1
	s_cmp_eq_u32 s84, 12
	s_cselect_b32 s83, s1, s9
	s_cselect_b32 s82, s33, s8
	s_cselect_b32 s9, s60, s75
	s_cselect_b32 s8, s61, s73
	s_add_i32 m0, s81, 0xc000
	ds_read_b128 v[186:189], v162
	ds_read_b128 v[190:193], v162 offset:1024
	ds_read_b128 v[194:197], v162 offset:2048
	ds_read_b128 v[198:201], v162 offset:3072
	ds_read_b128 v[202:205], v162 offset:4096
	ds_read_b128 v[208:211], v162 offset:5120
	ds_read_b128 v[212:215], v162 offset:6144
	ds_read_b128 v[216:219], v162 offset:7168
	global_load_lds_dwordx4 v138, s[6:7]
	s_add_i32 m0, s81, 0xe000
	s_nop 0
	global_load_lds_dwordx4 v140, s[6:7]
	s_waitcnt vmcnt(24)
	s_cmp_gt_u32 s91, 1
	s_cbranch_scc1 .Lpw_110_0
	s_waitcnt vmcnt(8)

; #define PG8_STAGE(bufoff, gbase, voff) do { _Pragma("unroll") for (int _i = 0; _i < 2; ++_i) \
;         __builtin_amdgcn_global_load_lds((const unsigned*)((const char*)(gbase) + (voff)[_i]), (PG8_LAS unsigned*)(lds + (bufoff) + ldsw + _i * 8192), 16, 0, 0); } while (0)
; #define PG8_LDA(dst, b, h) do { _Pragma("unroll") for (int m = 0; m < 4; ++m) _Pragma("unroll") for (int k = 0; k < 2; ++k) dst[m][k] = *(const PG8_LAS bf16x8*)(lds + PG8_SA(b, h) + aoff + m * 2048 + k * 1024); } while (0)
; #define PG8_LDB(dst, b, h) do { _Pragma("unroll") for (int n = 0; n < 2; ++n) _Pragma("unroll") for (int k = 0; k < 2; ++k) dst[n][k] = *(const PG8_LAS bf16x8*)(lds + PG8_SB(b, h) + boff + n * 2048 + k * 1024); } while (0)
; #define PG8_MMA(ai, bj, At, Bt) do { __builtin_amdgcn_s_setprio(1); _Pragma("unroll") for (int m = 0; m < 4; ++m) _Pragma("unroll") for (int n = 0; n < 2; ++n) _Pragma("unroll") for (int k = 0; k < 2; ++k) \
;         acc[ai][bj][m][n] = __builtin_amdgcn_mfma_f32_16x16x32_bf16(Bt[n][k], At[m][k], acc[ai][bj][m][n], 0, 0, 0); __builtin_amdgcn_s_setprio(0); } while (0)
; #define PG8_WAIT_V(n) asm volatile("s_waitcnt vmcnt(" #n ")" ::: "memory")
; #define PG8_WAIT_L(n) asm volatile("s_waitcnt lgkmcnt(" #n ")" ::: "memory")
; #define PG8_BAR __builtin_amdgcn_s_barrier()
; #define PG8_SCHED __builtin_amdgcn_sched_barrier(0)
; template <class Epi, class Sched, bool ALIGN_EPI = false, bool SP2 = false>
; __device__ __forceinline__ void gemm_phase(PG8_LAS unsigned char* lds, const Gemm g, const Sched& S, const Epi& E) {
;     ...
;             PG8_LDB(B0, 0, 0); PG8_LDB(B1, 0, 1); PG8_SCHED; PG8_LDA(At, 0, 0); PG8_STAGE(PG8_SA(1, 1), a1 + hstep, voffA);
;             PG8_WAIT_V(8); PG8_WAIT_L(0); PG8_BAR; PG8_MMA(0, 0, At, B0); PG8_MMA(0, 1, At, B1); PG8_BAR; PG8_SCHED;
;             PG8_LDA(At, 0, 1); PG8_STAGE(PG8_SB(0, 0), b2, voffB); PG8_STAGE(PG8_SB(0, 1), b2 + hstep, voffB); PG8_STAGE(PG8_SA(0, 0), a2, voffA);
.Lnl_110_0:
	s_barrier
	s_waitcnt lgkmcnt(0)
	v_mfma_f32_16x16x32_bf16 v[126:129], v[146:149], v[186:189], 0
	v_mfma_f32_16x16x32_bf16 v[122:125], v[154:157], v[186:189], 0
	v_mfma_f32_16x16x32_bf16 v[118:121], v[146:149], v[194:197], 0
	v_mfma_f32_16x16x32_bf16 v[114:117], v[154:157], v[194:197], 0
	v_mfma_f32_16x16x32_bf16 v[110:113], v[146:149], v[202:205], 0
	v_mfma_f32_16x16x32_bf16 v[106:109], v[154:157], v[202:205], 0
	v_mfma_f32_16x16x32_bf16 v[102:105], v[146:149], v[212:215], 0
	v_mfma_f32_16x16x32_bf16 v[98:101], v[154:157], v[212:215], 0
	v_mfma_f32_16x16x32_bf16 v[126:129], v[150:153], v[190:193], v[126:129]
	v_mfma_f32_16x16x32_bf16 v[122:125], v[166:169], v[190:193], v[122:125]
	v_mfma_f32_16x16x32_bf16 v[118:121], v[150:153], v[198:201], v[118:121]
	v_mfma_f32_16x16x32_bf16 v[114:117], v[166:169], v[198:201], v[114:117]
	v_mfma_f32_16x16x32_bf16 v[110:113], v[150:153], v[208:211], v[110:113]
	v_mfma_f32_16x16x32_bf16 v[106:109], v[166:169], v[208:211], v[106:109]
	v_mfma_f32_16x16x32_bf16 v[102:105], v[150:153], v[216:219], v[102:105]
	v_mfma_f32_16x16x32_bf16 v[98:101], v[166:169], v[216:219], v[98:101]
	v_mfma_f32_16x16x32_bf16 v[62:65], v[170:173], v[186:189], 0
	v_mfma_f32_16x16x32_bf16 v[58:61], v[178:181], v[186:189], 0
	v_mfma_f32_16x16x32_bf16 v[54:57], v[170:173], v[194:197], 0
	v_mfma_f32_16x16x32_bf16 v[50:53], v[178:181], v[194:197], 0
	v_mfma_f32_16x16x32_bf16 v[46:49], v[170:173], v[202:205], 0
	v_mfma_f32_16x16x32_bf16 v[42:45], v[178:181], v[202:205], 0
	v_mfma_f32_16x16x32_bf16 v[38:41], v[170:173], v[212:215], 0
	v_mfma_f32_16x16x32_bf16 v[34:37], v[178:181], v[212:215], 0
	v_mfma_f32_16x16x32_bf16 v[62:65], v[174:177], v[190:193], v[62:65]
	v_mfma_f32_16x16x32_bf16 v[58:61], v[182:185], v[190:193], v[58:61]
	v_mfma_f32_16x16x32_bf16 v[54:57], v[174:177], v[198:201], v[54:57]
	v_mfma_f32_16x16x32_bf16 v[50:53], v[182:185], v[198:201], v[50:53]
	v_mfma_f32_16x16x32_bf16 v[46:49], v[174:177], v[208:211], v[46:49]
	v_mfma_f32_16x16x32_bf16 v[42:45], v[182:185], v[208:211], v[42:45]
	v_mfma_f32_16x16x32_bf16 v[38:41], v[174:177], v[216:219], v[38:41]
	v_mfma_f32_16x16x32_bf16 v[34:37], v[182:185], v[216:219], v[34:37]
	s_barrier
	s_add_i32 s85, s30, s87
	s_mov_b32 m0, s85
	ds_read_b128 v[186:189], v162 offset:16384
	ds_read_b128 v[190:193], v162 offset:17408
	ds_read_b128 v[194:197], v162 offset:18432
	ds_read_b128 v[198:201], v162 offset:19456
	ds_read_b128 v[202:205], v162 offset:20480
	ds_read_b128 v[208:211], v162 offset:21504
	ds_read_b128 v[212:215], v162 offset:22528
	ds_read_b128 v[216:219], v162 offset:23552
	global_load_lds_dwordx4 v132, s[8:9]
	s_add_i32 m0, s85, 0x2000
	s_add_u32 vcc_lo, s8, 0x40000
	s_addc_u32 vcc_hi, s9, 0
	s_add_i32 s85, s31, s87
	global_load_lds_dwordx4 v136, s[8:9]
	s_mov_b32 m0, s85
	s_add_u32 s100, s82, 0x80
	s_addc_u32 s101, s83, 0
	global_load_lds_dwordx4 v132, vcc
	s_add_i32 m0, s85, 0x2000
	s_nop 0
	global_load_lds_dwordx4 v136, vcc
	s_mov_b32 m0, s81
	s_nop 0
	global_load_lds_dwordx4 v130, s[82:83]
	s_mov_b32 m0, s88
	s_nop 0
	global_load_lds_dwordx4 v134, s[82:83]
	s_waitcnt vmcnt(24)
	s_cmp_gt_u32 s91, 1
	s_cbranch_scc1 .Lpw_110_1
	s_waitcnt vmcnt(8)

; #define PG8_STAGE(bufoff, gbase, voff) do { _Pragma("unroll") for (int _i = 0; _i < 2; ++_i) \
;         __builtin_amdgcn_global_load_lds((const unsigned*)((const char*)(gbase) + (voff)[_i]), (PG8_LAS unsigned*)(lds + (bufoff) + ldsw + _i * 8192), 16, 0, 0); } while (0)
; #define PG8_LDA(dst, b, h) do { _Pragma("unroll") for (int m = 0; m < 4; ++m) _Pragma("unroll") for (int k = 0; k < 2; ++k) dst[m][k] = *(const PG8_LAS bf16x8*)(lds + PG8_SA(b, h) + aoff + m * 2048 + k * 1024); } while (0)
; template <class Epi, class Sched, bool ALIGN_EPI = false, bool SP2 = false>
; __device__ __forceinline__ void gemm_phase(PG8_LAS unsigned char* lds, const Gemm g, const Sched& S, const Epi& E) {
;     ...
;             PG8_LDA(At, 1, 1); PG8_STAGE(PG8_SB(1, 0), b3, voffB); PG8_STAGE(PG8_SB(1, 1), b3 + hstep, voffB); PG8_STAGE(PG8_SA(1, 0), a3, voffA);
.Lnl_110_2:
	s_barrier
	s_waitcnt lgkmcnt(0)
	v_mfma_f32_16x16x32_bf16 v[126:129], v[146:149], v[186:189], v[126:129]
	v_mfma_f32_16x16x32_bf16 v[122:125], v[154:157], v[186:189], v[122:125]
	v_mfma_f32_16x16x32_bf16 v[118:121], v[146:149], v[194:197], v[118:121]
	v_mfma_f32_16x16x32_bf16 v[114:117], v[154:157], v[194:197], v[114:117]
	v_mfma_f32_16x16x32_bf16 v[110:113], v[146:149], v[202:205], v[110:113]
	v_mfma_f32_16x16x32_bf16 v[106:109], v[154:157], v[202:205], v[106:109]
	v_mfma_f32_16x16x32_bf16 v[102:105], v[146:149], v[212:215], v[102:105]
	v_mfma_f32_16x16x32_bf16 v[98:101], v[154:157], v[212:215], v[98:101]
	v_mfma_f32_16x16x32_bf16 v[126:129], v[150:153], v[190:193], v[126:129]
	v_mfma_f32_16x16x32_bf16 v[122:125], v[166:169], v[190:193], v[122:125]
	v_mfma_f32_16x16x32_bf16 v[118:121], v[150:153], v[198:201], v[118:121]
	v_mfma_f32_16x16x32_bf16 v[114:117], v[166:169], v[198:201], v[114:117]
	v_mfma_f32_16x16x32_bf16 v[110:113], v[150:153], v[208:211], v[110:113]
	v_mfma_f32_16x16x32_bf16 v[106:109], v[166:169], v[208:211], v[106:109]
	v_mfma_f32_16x16x32_bf16 v[102:105], v[150:153], v[216:219], v[102:105]
	v_mfma_f32_16x16x32_bf16 v[98:101], v[166:169], v[216:219], v[98:101]
	v_mfma_f32_16x16x32_bf16 v[62:65], v[170:173], v[186:189], v[62:65]
	v_mfma_f32_16x16x32_bf16 v[58:61], v[178:181], v[186:189], v[58:61]
	v_mfma_f32_16x16x32_bf16 v[54:57], v[170:173], v[194:197], v[54:57]
	v_mfma_f32_16x16x32_bf16 v[50:53], v[178:181], v[194:197], v[50:53]
	v_mfma_f32_16x16x32_bf16 v[46:49], v[170:173], v[202:205], v[46:49]
	v_mfma_f32_16x16x32_bf16 v[42:45], v[178:181], v[202:205], v[42:45]
	v_mfma_f32_16x16x32_bf16 v[38:41], v[170:173], v[212:215], v[38:41]
	v_mfma_f32_16x16x32_bf16 v[34:37], v[178:181], v[212:215], v[34:37]
	v_mfma_f32_16x16x32_bf16 v[62:65], v[174:177], v[190:193], v[62:65]
	v_mfma_f32_16x16x32_bf16 v[58:61], v[182:185], v[190:193], v[58:61]
	v_mfma_f32_16x16x32_bf16 v[54:57], v[174:177], v[198:201], v[54:57]
	v_mfma_f32_16x16x32_bf16 v[50:53], v[182:185], v[198:201], v[50:53]
	v_mfma_f32_16x16x32_bf16 v[46:49], v[174:177], v[208:211], v[46:49]
	v_mfma_f32_16x16x32_bf16 v[42:45], v[182:185], v[208:211], v[42:45]
	v_mfma_f32_16x16x32_bf16 v[38:41], v[174:177], v[216:219], v[38:41]
	v_mfma_f32_16x16x32_bf16 v[34:37], v[182:185], v[216:219], v[34:37]
	s_barrier
	s_add_i32 s82, s85, s87
	s_mov_b32 m0, s82
	ds_read_b128 v[186:189], v162 offset:49152
	ds_read_b128 v[190:193], v162 offset:50176
	ds_read_b128 v[194:197], v162 offset:51200
	ds_read_b128 v[198:201], v162 offset:52224
	ds_read_b128 v[202:205], v162 offset:53248
	ds_read_b128 v[208:211], v162 offset:54272
	ds_read_b128 v[212:215], v162 offset:55296
	ds_read_b128 v[216:219], v162 offset:56320
	s_add_u32 s98, s8, s26
	s_addc_u32 s99, s9, s27
	global_load_lds_dwordx4 v132, s[98:99]
	s_add_i32 m0, s82, 0x2000
	s_add_u32 s8, s8, 0x40080
	s_addc_u32 s9, s9, 0
	s_add_i32 s82, vcc_lo, s87
	global_load_lds_dwordx4 v136, s[98:99]
	s_mov_b32 m0, s82
	s_nop 0
	global_load_lds_dwordx4 v132, s[8:9]
	s_add_i32 m0, s82, 0x2000
	s_nop 0
	global_load_lds_dwordx4 v136, s[8:9]
	s_mov_b32 m0, s92
	s_nop 0
	global_load_lds_dwordx4 v130, s[100:101]
	s_mov_b32 m0, s93
	s_nop 0
	global_load_lds_dwordx4 v134, s[100:101]
	s_waitcnt vmcnt(8)
	s_bitcmp1_b32 s68, 0
	s_cbranch_scc1 .Lnl_110_3
	s_waitcnt lgkmcnt(0)

; #define PG8_STAGE(bufoff, gbase, voff) do { _Pragma("unroll") for (int _i = 0; _i < 2; ++_i) \
;         __builtin_amdgcn_global_load_lds((const unsigned*)((const char*)(gbase) + (voff)[_i]), (PG8_LAS unsigned*)(lds + (bufoff) + ldsw + _i * 8192), 16, 0, 0); } while (0)
; #define PG8_LDA(dst, b, h) do { _Pragma("unroll") for (int m = 0; m < 4; ++m) _Pragma("unroll") for (int k = 0; k < 2; ++k) dst[m][k] = *(const PG8_LAS bf16x8*)(lds + PG8_SA(b, h) + aoff + m * 2048 + k * 1024); } while (0)
; #define PG8_LDB(dst, b, h) do { _Pragma("unroll") for (int n = 0; n < 2; ++n) _Pragma("unroll") for (int k = 0; k < 2; ++k) dst[n][k] = *(const PG8_LAS bf16x8*)(lds + PG8_SB(b, h) + boff + n * 2048 + k * 1024); } while (0)
; #define PG8_MMA(ai, bj, At, Bt) do { __builtin_amdgcn_s_setprio(1); _Pragma("unroll") for (int m = 0; m < 4; ++m) _Pragma("unroll") for (int n = 0; n < 2; ++n) _Pragma("unroll") for (int k = 0; k < 2; ++k) \
;         acc[ai][bj][m][n] = __builtin_amdgcn_mfma_f32_16x16x32_bf16(Bt[n][k], At[m][k], acc[ai][bj][m][n], 0, 0, 0); __builtin_amdgcn_s_setprio(0); } while (0)
; #define PG8_WAIT_V(n) asm volatile("s_waitcnt vmcnt(" #n ")" ::: "memory")
; #define PG8_WAIT_L(n) asm volatile("s_waitcnt lgkmcnt(" #n ")" ::: "memory")
; #define PG8_BAR __builtin_amdgcn_s_barrier()
; #define PG8_SCHED __builtin_amdgcn_sched_barrier(0)
; template <class Epi, class Sched, bool ALIGN_EPI = false, bool SP2 = false>
; __device__ __forceinline__ void gemm_phase(PG8_LAS unsigned char* lds, const Gemm g, const Sched& S, const Epi& E) {
;     ...
;             PG8_LDB(B0, 0, 0); PG8_LDB(B1, 0, 1); PG8_SCHED; PG8_LDA(At, 0, 0); PG8_STAGE(PG8_SA(1, 1), a1 + hstep, voffA);
;             PG8_WAIT_V(8); PG8_WAIT_L(0); PG8_BAR; PG8_MMA(0, 0, At, B0); PG8_MMA(0, 1, At, B1); PG8_BAR; PG8_SCHED;
;             PG8_LDA(At, 0, 1); PG8_STAGE(PG8_SB(0, 0), b2, voffB); PG8_STAGE(PG8_SB(0, 1), b2 + hstep, voffB); PG8_STAGE(PG8_SA(0, 0), a2, voffA);
.LBB0_110:
	ds_read_b128 v[146:149], v160
	ds_read_b128 v[150:153], v160 offset:1024
	ds_read_b128 v[154:157], v160 offset:2048
	ds_read_b128 v[166:169], v160 offset:3072
	ds_read_b128 v[170:173], v161
	ds_read_b128 v[174:177], v161 offset:1024
	ds_read_b128 v[178:181], v161 offset:2048
	ds_read_b128 v[182:185], v161 offset:3072
	s_add_u32 s8, s6, 0xfffc0080
	s_addc_u32 s9, s7, -1
	s_cmp_eq_u32 s84, 12
	s_cselect_b32 s83, s1, s9
	s_cselect_b32 s82, s33, s8
	s_cselect_b32 s9, s60, s75
	s_cselect_b32 s8, s61, s73
	s_add_i32 m0, s81, 0xc000
	ds_read_b128 v[186:189], v162
	ds_read_b128 v[190:193], v162 offset:1024
	ds_read_b128 v[194:197], v162 offset:2048
	ds_read_b128 v[198:201], v162 offset:3072
	ds_read_b128 v[202:205], v162 offset:4096
	ds_read_b128 v[208:211], v162 offset:5120
	ds_read_b128 v[212:215], v162 offset:6144
	ds_read_b128 v[216:219], v162 offset:7168
	global_load_lds_dwordx4 v138, s[6:7]
	s_add_i32 m0, s81, 0xe000
	s_nop 0
	global_load_lds_dwordx4 v140, s[6:7]
	s_waitcnt vmcnt(8)
	s_bitcmp1_b32 s68, 0
	s_cbranch_scc1 .Lnl_110_4
	s_waitcnt lgkmcnt(0)
.Lnl_110_4:
	s_barrier
	s_waitcnt lgkmcnt(0)
	v_mfma_f32_16x16x32_bf16 v[126:129], v[146:149], v[186:189], v[126:129]
	v_mfma_f32_16x16x32_bf16 v[122:125], v[154:157], v[186:189], v[122:125]
	v_mfma_f32_16x16x32_bf16 v[118:121], v[146:149], v[194:197], v[118:121]
	v_mfma_f32_16x16x32_bf16 v[114:117], v[154:157], v[194:197], v[114:117]
	v_mfma_f32_16x16x32_bf16 v[110:113], v[146:149], v[202:205], v[110:113]
	v_mfma_f32_16x16x32_bf16 v[106:109], v[154:157], v[202:205], v[106:109]
	v_mfma_f32_16x16x32_bf16 v[102:105], v[146:149], v[212:215], v[102:105]
	v_mfma_f32_16x16x32_bf16 v[98:101], v[154:157], v[212:215], v[98:101]
	v_mfma_f32_16x16x32_bf16 v[126:129], v[150:153], v[190:193], v[126:129]
	v_mfma_f32_16x16x32_bf16 v[122:125], v[166:169], v[190:193], v[122:125]
	v_mfma_f32_16x16x32_bf16 v[118:121], v[150:153], v[198:201], v[118:121]
	v_mfma_f32_16x16x32_bf16 v[114:117], v[166:169], v[198:201], v[114:117]
	v_mfma_f32_16x16x32_bf16 v[110:113], v[150:153], v[208:211], v[110:113]
	v_mfma_f32_16x16x32_bf16 v[106:109], v[166:169], v[208:211], v[106:109]
	v_mfma_f32_16x16x32_bf16 v[102:105], v[150:153], v[216:219], v[102:105]
	v_mfma_f32_16x16x32_bf16 v[98:101], v[166:169], v[216:219], v[98:101]
	v_mfma_f32_16x16x32_bf16 v[62:65], v[170:173], v[186:189], v[62:65]
	v_mfma_f32_16x16x32_bf16 v[58:61], v[178:181], v[186:189], v[58:61]
	v_mfma_f32_16x16x32_bf16 v[54:57], v[170:173], v[194:197], v[54:57]
	v_mfma_f32_16x16x32_bf16 v[50:53], v[178:181], v[194:197], v[50:53]
	v_mfma_f32_16x16x32_bf16 v[46:49], v[170:173], v[202:205], v[46:49]
	v_mfma_f32_16x16x32_bf16 v[42:45], v[178:181], v[202:205], v[42:45]
	v_mfma_f32_16x16x32_bf16 v[38:41], v[170:173], v[212:215], v[38:41]
	v_mfma_f32_16x16x32_bf16 v[34:37], v[178:181], v[212:215], v[34:37]
	v_mfma_f32_16x16x32_bf16 v[62:65], v[174:177], v[190:193], v[62:65]
	v_mfma_f32_16x16x32_bf16 v[58:61], v[182:185], v[190:193], v[58:61]
	v_mfma_f32_16x16x32_bf16 v[54:57], v[174:177], v[198:201], v[54:57]
	v_mfma_f32_16x16x32_bf16 v[50:53], v[182:185], v[198:201], v[50:53]
	v_mfma_f32_16x16x32_bf16 v[46:49], v[174:177], v[208:211], v[46:49]
	v_mfma_f32_16x16x32_bf16 v[42:45], v[182:185], v[208:211], v[42:45]
	v_mfma_f32_16x16x32_bf16 v[38:41], v[174:177], v[216:219], v[38:41]
	v_mfma_f32_16x16x32_bf16 v[34:37], v[182:185], v[216:219], v[34:37]
	s_barrier
	s_add_i32 s85, s30, s87
	s_mov_b32 m0, s85
	ds_read_b128 v[186:189], v162 offset:16384
	ds_read_b128 v[190:193], v162 offset:17408
	ds_read_b128 v[194:197], v162 offset:18432
	ds_read_b128 v[198:201], v162 offset:19456
	ds_read_b128 v[202:205], v162 offset:20480
	ds_read_b128 v[208:211], v162 offset:21504
	ds_read_b128 v[212:215], v162 offset:22528
	ds_read_b128 v[216:219], v162 offset:23552
	global_load_lds_dwordx4 v132, s[8:9]
	s_add_i32 m0, s85, 0x2000
	s_add_u32 vcc_lo, s8, 0x40000
	s_addc_u32 vcc_hi, s9, 0
	s_add_i32 s85, s31, s87
	global_load_lds_dwordx4 v136, s[8:9]
	s_mov_b32 m0, s85
	s_add_u32 s100, s82, 0x80
	s_addc_u32 s101, s83, 0
	global_load_lds_dwordx4 v132, vcc
	s_add_i32 m0, s85, 0x2000
	s_nop 0
	global_load_lds_dwordx4 v136, vcc
	s_mov_b32 m0, s81
	s_nop 0
	global_load_lds_dwordx4 v130, s[82:83]
	s_mov_b32 m0, s88
	s_nop 0
	global_load_lds_dwordx4 v134, s[82:83]
	s_waitcnt vmcnt(8)
	s_bitcmp1_b32 s68, 0
	s_cbranch_scc1 .Lnl_110_5
	s_waitcnt lgkmcnt(0)

; #define PG8_STAGE(bufoff, gbase, voff) do { _Pragma("unroll") for (int _i = 0; _i < 2; ++_i) \
;         __builtin_amdgcn_global_load_lds((const unsigned*)((const char*)(gbase) + (voff)[_i]), (PG8_LAS unsigned*)(lds + (bufoff) + ldsw + _i * 8192), 16, 0, 0); } while (0)
; #define PG8_LDA(dst, b, h) do { _Pragma("unroll") for (int m = 0; m < 4; ++m) _Pragma("unroll") for (int k = 0; k < 2; ++k) dst[m][k] = *(const PG8_LAS bf16x8*)(lds + PG8_SA(b, h) + aoff + m * 2048 + k * 1024); } while (0)
; #define PG8_LDB(dst, b, h) do { _Pragma("unroll") for (int n = 0; n < 2; ++n) _Pragma("unroll") for (int k = 0; k < 2; ++k) dst[n][k] = *(const PG8_LAS bf16x8*)(lds + PG8_SB(b, h) + boff + n * 2048 + k * 1024); } while (0)
; #define PG8_MMA(ai, bj, At, Bt) do { __builtin_amdgcn_s_setprio(1); _Pragma("unroll") for (int m = 0; m < 4; ++m) _Pragma("unroll") for (int n = 0; n < 2; ++n) _Pragma("unroll") for (int k = 0; k < 2; ++k) \
;         acc[ai][bj][m][n] = __builtin_amdgcn_mfma_f32_16x16x32_bf16(Bt[n][k], At[m][k], acc[ai][bj][m][n], 0, 0, 0); __builtin_amdgcn_s_setprio(0); } while (0)
; #define PG8_BAR __builtin_amdgcn_s_barrier()
; template <class Epi, class Sched, bool ALIGN_EPI = false, bool SP2 = false>
; __device__ __forceinline__ void gemm_phase(PG8_LAS unsigned char* lds, const Gemm g, const Sched& S, const Epi& E) {
;     ...
;         const bool has_next = S.next(ui + 1, nxt);
;         const char* nA = has_next ? (const char*)g.A + (size_t)nxt.pm * tstep : cA; const char* nB = has_next ? (const char*)g.Bt + (size_t)nxt.pn * tstep : cB;
;         for (int t = 0; t < nt; t += 2) {
;             const bool last = (t == nt - 2);
;             const char* a1 = cA + (size_t)(t + 1) * kstep;
;             const char* a2 = last ? nA : cA + (size_t)(t + 2) * kstep; const char* b2 = last ? nB : cB + (size_t)(t + 2) * kstep;
;             const char* a3 = a2 + kstep; const char* b3 = b2 + kstep;
;             if (last && has_next) S.a_ready(nxt);
;             if constexpr (SP2) {
;             PG8_LDB(B0, 0, 0); PG8_LDB(B1, 0, 1); PG8_SCHED; PG8_LDA(At, 0, 0); PG8_STAGE(PG8_SA(1, 1), a1 + hstep, voffA);
;             PG8_WAIT_V(8); PG8_WAIT_L(0); PG8_BAR; PG8_MMA(0, 0, At, B0); PG8_MMA(0, 1, At, B1); PG8_BAR; PG8_SCHED;
;             PG8_LDA(At, 0, 1); PG8_STAGE(PG8_SB(0, 0), b2, voffB); PG8_STAGE(PG8_SB(0, 1), b2 + hstep, voffB); PG8_STAGE(PG8_SA(0, 0), a2, voffA);
.LBB0_645:
	s_ashr_i32 s21, s20, 31
	s_lshl_b64 s[22:23], s[20:21], 19
	s_add_u32 s22, s0, s22
	s_addc_u32 s23, s1, s23
	s_and_b64 s[24:25], s[6:7], exec
	s_cselect_b32 s21, s23, s45
	s_cselect_b32 s27, s22, s44
	s_ashr_i32 s19, s18, 31
	s_lshl_b64 s[24:25], s[18:19], 19
	s_add_u32 s24, s64, s24
	s_addc_u32 s25, s65, s25
	s_and_b64 s[48:49], s[6:7], exec
	s_cselect_b32 s19, s25, s47
	s_cselect_b32 s33, s24, s46
	s_add_u32 s44, s44, 0x40080
	s_addc_u32 s45, s45, 0
	s_add_u32 s71, s46, 0x100
	s_addc_u32 s72, s47, 0
	s_mov_b32 s73, -2
	s_waitcnt lgkmcnt(0)
	ds_read_b128 v[148:151], v152
	ds_read_b128 v[156:159], v152 offset:1024
	ds_read_b128 v[160:163], v152 offset:2048
	ds_read_b128 v[164:167], v152 offset:3072
	ds_read_b128 v[168:171], v153
	ds_read_b128 v[172:175], v153 offset:1024
	ds_read_b128 v[176:179], v153 offset:2048
	ds_read_b128 v[180:183], v153 offset:3072
	s_add_u32 s46, s44, 0xfffc0080
	s_addc_u32 s47, s45, -1
	s_cmp_eq_u32 s73, 12
	s_cselect_b32 s49, s21, s47
	s_cselect_b32 s48, s27, s46
	s_cselect_b32 s47, s19, s72
	s_cselect_b32 s46, s33, s71
	s_add_i32 m0, s31, 0xc000
	ds_read_b128 v[184:187], v154
	ds_read_b128 v[188:191], v154 offset:1024
	ds_read_b128 v[192:195], v154 offset:2048
	ds_read_b128 v[196:199], v154 offset:3072
	ds_read_b128 v[200:203], v154 offset:4096
	ds_read_b128 v[208:211], v154 offset:5120
	ds_read_b128 v[212:215], v154 offset:6144
	ds_read_b128 v[216:219], v154 offset:7168
	global_load_lds_dwordx4 v140, s[44:45]
	s_add_i32 m0, s31, 0xe000
	s_nop 0
	global_load_lds_dwordx4 v142, s[44:45]
	s_waitcnt vmcnt(8)
	s_bitcmp1_b32 s16, 0
	s_cbranch_scc1 .Lnl_646_0
	s_waitcnt lgkmcnt(0)
.Lnl_646_0:
	s_barrier
	s_waitcnt lgkmcnt(0)
	v_mfma_f32_16x16x32_bf16 v[126:129], v[148:151], v[184:187], 0
	v_mfma_f32_16x16x32_bf16 v[122:125], v[160:163], v[184:187], 0
	v_mfma_f32_16x16x32_bf16 v[110:113], v[148:151], v[192:195], 0
	v_mfma_f32_16x16x32_bf16 v[106:109], v[160:163], v[192:195], 0
	v_mfma_f32_16x16x32_bf16 v[94:97], v[148:151], v[200:203], 0
	v_mfma_f32_16x16x32_bf16 v[90:93], v[160:163], v[200:203], 0
	v_mfma_f32_16x16x32_bf16 v[78:81], v[148:151], v[212:215], 0
	v_mfma_f32_16x16x32_bf16 v[74:77], v[160:163], v[212:215], 0
	v_mfma_f32_16x16x32_bf16 v[126:129], v[156:159], v[188:191], v[126:129]
	v_mfma_f32_16x16x32_bf16 v[122:125], v[164:167], v[188:191], v[122:125]
	v_mfma_f32_16x16x32_bf16 v[110:113], v[156:159], v[196:199], v[110:113]
	v_mfma_f32_16x16x32_bf16 v[106:109], v[164:167], v[196:199], v[106:109]
	v_mfma_f32_16x16x32_bf16 v[94:97], v[156:159], v[208:211], v[94:97]
	v_mfma_f32_16x16x32_bf16 v[90:93], v[164:167], v[208:211], v[90:93]
	v_mfma_f32_16x16x32_bf16 v[78:81], v[156:159], v[216:219], v[78:81]
	v_mfma_f32_16x16x32_bf16 v[74:77], v[164:167], v[216:219], v[74:77]
	v_mfma_f32_16x16x32_bf16 v[118:121], v[168:171], v[184:187], 0
	v_mfma_f32_16x16x32_bf16 v[114:117], v[176:179], v[184:187], 0
	v_mfma_f32_16x16x32_bf16 v[102:105], v[168:171], v[192:195], 0
	v_mfma_f32_16x16x32_bf16 v[98:101], v[176:179], v[192:195], 0
	v_mfma_f32_16x16x32_bf16 v[86:89], v[168:171], v[200:203], 0
	v_mfma_f32_16x16x32_bf16 v[82:85], v[176:179], v[200:203], 0
	v_mfma_f32_16x16x32_bf16 v[70:73], v[168:171], v[212:215], 0
	v_mfma_f32_16x16x32_bf16 v[66:69], v[176:179], v[212:215], 0
	v_mfma_f32_16x16x32_bf16 v[118:121], v[172:175], v[188:191], v[118:121]
	v_mfma_f32_16x16x32_bf16 v[114:117], v[180:183], v[188:191], v[114:117]
	v_mfma_f32_16x16x32_bf16 v[102:105], v[172:175], v[196:199], v[102:105]
	v_mfma_f32_16x16x32_bf16 v[98:101], v[180:183], v[196:199], v[98:101]
	v_mfma_f32_16x16x32_bf16 v[86:89], v[172:175], v[208:211], v[86:89]
	v_mfma_f32_16x16x32_bf16 v[82:85], v[180:183], v[208:211], v[82:85]
	v_mfma_f32_16x16x32_bf16 v[70:73], v[172:175], v[216:219], v[70:73]
	v_mfma_f32_16x16x32_bf16 v[66:69], v[180:183], v[216:219], v[66:69]
	s_barrier
	s_add_i32 s74, s68, s30
	s_mov_b32 m0, s74
	ds_read_b128 v[184:187], v154 offset:16384
	ds_read_b128 v[188:191], v154 offset:17408
	ds_read_b128 v[192:195], v154 offset:18432
	ds_read_b128 v[196:199], v154 offset:19456
	ds_read_b128 v[200:203], v154 offset:20480
	ds_read_b128 v[208:211], v154 offset:21504
	ds_read_b128 v[212:215], v154 offset:22528
	ds_read_b128 v[216:219], v154 offset:23552
	global_load_lds_dwordx4 v132, s[46:47]
	s_add_i32 m0, s74, 0x2000
	s_add_u32 s74, s46, 0x40000
	s_addc_u32 s75, s47, 0
	s_add_i32 s76, s69, s30
	global_load_lds_dwordx4 v136, s[46:47]
	s_mov_b32 m0, s76
	s_add_u32 s100, s48, 0x80
	s_addc_u32 s101, s49, 0
	global_load_lds_dwordx4 v132, s[74:75]
	s_add_i32 m0, s76, 0x2000
	s_nop 0
	global_load_lds_dwordx4 v136, s[74:75]
	s_mov_b32 m0, s31
	s_nop 0
	global_load_lds_dwordx4 v130, s[48:49]
	s_mov_b32 m0, s50
	s_nop 0
	global_load_lds_dwordx4 v134, s[48:49]
	s_waitcnt vmcnt(8)
	s_bitcmp1_b32 s16, 0
	s_cbranch_scc1 .Lnl_646_1
	s_waitcnt lgkmcnt(0)

; #define PG8_STAGE(bufoff, gbase, voff) do { _Pragma("unroll") for (int _i = 0; _i < 2; ++_i) \
;         __builtin_amdgcn_global_load_lds((const unsigned*)((const char*)(gbase) + (voff)[_i]), (PG8_LAS unsigned*)(lds + (bufoff) + ldsw + _i * 8192), 16, 0, 0); } while (0)
; #define PG8_LDA(dst, b, h) do { _Pragma("unroll") for (int m = 0; m < 4; ++m) _Pragma("unroll") for (int k = 0; k < 2; ++k) dst[m][k] = *(const PG8_LAS bf16x8*)(lds + PG8_SA(b, h) + aoff + m * 2048 + k * 1024); } while (0)
; template <class Epi, class Sched, bool ALIGN_EPI = false, bool SP2 = false>
; __device__ __forceinline__ void gemm_phase(PG8_LAS unsigned char* lds, const Gemm g, const Sched& S, const Epi& E) {
;     ...
;             PG8_LDA(At, 1, 1); PG8_STAGE(PG8_SB(1, 0), b3, voffB); PG8_STAGE(PG8_SB(1, 1), b3 + hstep, voffB); PG8_STAGE(PG8_SA(1, 0), a3, voffA);
.Lnl_646_2:
	s_barrier
	s_waitcnt lgkmcnt(0)
	v_mfma_f32_16x16x32_bf16 v[126:129], v[148:151], v[184:187], v[126:129]
	v_mfma_f32_16x16x32_bf16 v[122:125], v[160:163], v[184:187], v[122:125]
	v_mfma_f32_16x16x32_bf16 v[110:113], v[148:151], v[192:195], v[110:113]
	v_mfma_f32_16x16x32_bf16 v[106:109], v[160:163], v[192:195], v[106:109]
	v_mfma_f32_16x16x32_bf16 v[94:97], v[148:151], v[200:203], v[94:97]
	v_mfma_f32_16x16x32_bf16 v[90:93], v[160:163], v[200:203], v[90:93]
	v_mfma_f32_16x16x32_bf16 v[78:81], v[148:151], v[212:215], v[78:81]
	v_mfma_f32_16x16x32_bf16 v[74:77], v[160:163], v[212:215], v[74:77]
	v_mfma_f32_16x16x32_bf16 v[126:129], v[156:159], v[188:191], v[126:129]
	v_mfma_f32_16x16x32_bf16 v[122:125], v[164:167], v[188:191], v[122:125]
	v_mfma_f32_16x16x32_bf16 v[110:113], v[156:159], v[196:199], v[110:113]
	v_mfma_f32_16x16x32_bf16 v[106:109], v[164:167], v[196:199], v[106:109]
	v_mfma_f32_16x16x32_bf16 v[94:97], v[156:159], v[208:211], v[94:97]
	v_mfma_f32_16x16x32_bf16 v[90:93], v[164:167], v[208:211], v[90:93]
	v_mfma_f32_16x16x32_bf16 v[78:81], v[156:159], v[216:219], v[78:81]
	v_mfma_f32_16x16x32_bf16 v[74:77], v[164:167], v[216:219], v[74:77]
	v_mfma_f32_16x16x32_bf16 v[118:121], v[168:171], v[184:187], v[118:121]
	v_mfma_f32_16x16x32_bf16 v[114:117], v[176:179], v[184:187], v[114:117]
	v_mfma_f32_16x16x32_bf16 v[102:105], v[168:171], v[192:195], v[102:105]
	v_mfma_f32_16x16x32_bf16 v[98:101], v[176:179], v[192:195], v[98:101]
	v_mfma_f32_16x16x32_bf16 v[86:89], v[168:171], v[200:203], v[86:89]
	v_mfma_f32_16x16x32_bf16 v[82:85], v[176:179], v[200:203], v[82:85]
	v_mfma_f32_16x16x32_bf16 v[70:73], v[168:171], v[212:215], v[70:73]
	v_mfma_f32_16x16x32_bf16 v[66:69], v[176:179], v[212:215], v[66:69]
	v_mfma_f32_16x16x32_bf16 v[118:121], v[172:175], v[188:191], v[118:121]
	v_mfma_f32_16x16x32_bf16 v[114:117], v[180:183], v[188:191], v[114:117]
	v_mfma_f32_16x16x32_bf16 v[102:105], v[172:175], v[196:199], v[102:105]
	v_mfma_f32_16x16x32_bf16 v[98:101], v[180:183], v[196:199], v[98:101]
	v_mfma_f32_16x16x32_bf16 v[86:89], v[172:175], v[208:211], v[86:89]
	v_mfma_f32_16x16x32_bf16 v[82:85], v[180:183], v[208:211], v[82:85]
	v_mfma_f32_16x16x32_bf16 v[70:73], v[172:175], v[216:219], v[70:73]
	v_mfma_f32_16x16x32_bf16 v[66:69], v[180:183], v[216:219], v[66:69]
	s_barrier
	s_add_i32 s48, s74, s30
	s_mov_b32 m0, s48
	ds_read_b128 v[184:187], v154 offset:49152
	ds_read_b128 v[188:191], v154 offset:50176
	ds_read_b128 v[192:195], v154 offset:51200
	ds_read_b128 v[196:199], v154 offset:52224
	ds_read_b128 v[200:203], v154 offset:53248
	ds_read_b128 v[208:211], v154 offset:54272
	ds_read_b128 v[212:215], v154 offset:55296
	ds_read_b128 v[216:219], v154 offset:56320
	s_add_u32 s98, s46, s14
	s_addc_u32 s99, s47, s15
	global_load_lds_dwordx4 v132, s[98:99]
	s_add_i32 m0, s48, 0x2000
	s_add_u32 s46, s46, 0x40080
	s_addc_u32 s47, s47, 0
	s_add_i32 s48, s75, s30
	global_load_lds_dwordx4 v136, s[98:99]
	s_mov_b32 m0, s48
	s_nop 0
	global_load_lds_dwordx4 v132, s[46:47]
	s_add_i32 m0, s48, 0x2000
	s_nop 0
	global_load_lds_dwordx4 v136, s[46:47]
	s_mov_b32 m0, s62
	s_nop 0
	global_load_lds_dwordx4 v130, s[100:101]
	s_mov_b32 m0, s63
	s_nop 0
	global_load_lds_dwordx4 v134, s[100:101]
	s_waitcnt vmcnt(8)
	s_bitcmp1_b32 s16, 0
	s_cbranch_scc1 .Lnl_646_3
	s_waitcnt lgkmcnt(0)

; #define PG8_STAGE(bufoff, gbase, voff) do { _Pragma("unroll") for (int _i = 0; _i < 2; ++_i) \
;         __builtin_amdgcn_global_load_lds((const unsigned*)((const char*)(gbase) + (voff)[_i]), (PG8_LAS unsigned*)(lds + (bufoff) + ldsw + _i * 8192), 16, 0, 0); } while (0)
; #define PG8_LDA(dst, b, h) do { _Pragma("unroll") for (int m = 0; m < 4; ++m) _Pragma("unroll") for (int k = 0; k < 2; ++k) dst[m][k] = *(const PG8_LAS bf16x8*)(lds + PG8_SA(b, h) + aoff + m * 2048 + k * 1024); } while (0)
; #define PG8_LDB(dst, b, h) do { _Pragma("unroll") for (int n = 0; n < 2; ++n) _Pragma("unroll") for (int k = 0; k < 2; ++k) dst[n][k] = *(const PG8_LAS bf16x8*)(lds + PG8_SB(b, h) + boff + n * 2048 + k * 1024); } while (0)
; #define PG8_MMA(ai, bj, At, Bt) do { __builtin_amdgcn_s_setprio(1); _Pragma("unroll") for (int m = 0; m < 4; ++m) _Pragma("unroll") for (int n = 0; n < 2; ++n) _Pragma("unroll") for (int k = 0; k < 2; ++k) \
;         acc[ai][bj][m][n] = __builtin_amdgcn_mfma_f32_16x16x32_bf16(Bt[n][k], At[m][k], acc[ai][bj][m][n], 0, 0, 0); __builtin_amdgcn_s_setprio(0); } while (0)
; #define PG8_WAIT_V(n) asm volatile("s_waitcnt vmcnt(" #n ")" ::: "memory")
; #define PG8_WAIT_L(n) asm volatile("s_waitcnt lgkmcnt(" #n ")" ::: "memory")
; #define PG8_BAR __builtin_amdgcn_s_barrier()
; #define PG8_SCHED __builtin_amdgcn_sched_barrier(0)
; template <class Epi, class Sched, bool ALIGN_EPI = false, bool SP2 = false>
; __device__ __forceinline__ void gemm_phase(PG8_LAS unsigned char* lds, const Gemm g, const Sched& S, const Epi& E) {
;     ...
;             PG8_LDB(B0, 0, 0); PG8_LDB(B1, 0, 1); PG8_SCHED; PG8_LDA(At, 0, 0); PG8_STAGE(PG8_SA(1, 1), a1 + hstep, voffA);
;             PG8_WAIT_V(8); PG8_WAIT_L(0); PG8_BAR; PG8_MMA(0, 0, At, B0); PG8_MMA(0, 1, At, B1); PG8_BAR; PG8_SCHED;
;             PG8_LDA(At, 0, 1); PG8_STAGE(PG8_SB(0, 0), b2, voffB); PG8_STAGE(PG8_SB(0, 1), b2 + hstep, voffB); PG8_STAGE(PG8_SA(0, 0), a2, voffA);
.LBB0_646:
	ds_read_b128 v[148:151], v152
	ds_read_b128 v[156:159], v152 offset:1024
	ds_read_b128 v[160:163], v152 offset:2048
	ds_read_b128 v[164:167], v152 offset:3072
	ds_read_b128 v[168:171], v153
	ds_read_b128 v[172:175], v153 offset:1024
	ds_read_b128 v[176:179], v153 offset:2048
	ds_read_b128 v[180:183], v153 offset:3072
	s_add_u32 s46, s44, 0xfffc0080
	s_addc_u32 s47, s45, -1
	s_cmp_eq_u32 s73, 12
	s_cselect_b32 s49, s21, s47
	s_cselect_b32 s48, s27, s46
	s_cselect_b32 s47, s19, s72
	s_cselect_b32 s46, s33, s71
	s_add_i32 m0, s31, 0xc000
	ds_read_b128 v[184:187], v154
	ds_read_b128 v[188:191], v154 offset:1024
	ds_read_b128 v[192:195], v154 offset:2048
	ds_read_b128 v[196:199], v154 offset:3072
	ds_read_b128 v[200:203], v154 offset:4096
	ds_read_b128 v[208:211], v154 offset:5120
	ds_read_b128 v[212:215], v154 offset:6144
	ds_read_b128 v[216:219], v154 offset:7168
	global_load_lds_dwordx4 v140, s[44:45]
	s_add_i32 m0, s31, 0xe000
	s_nop 0
	global_load_lds_dwordx4 v142, s[44:45]
	s_waitcnt vmcnt(8)
	s_bitcmp1_b32 s16, 0
	s_cbranch_scc1 .Lnl_646_4
	s_waitcnt lgkmcnt(0)
.Lnl_646_4:
	s_barrier
	s_waitcnt lgkmcnt(0)
	v_mfma_f32_16x16x32_bf16 v[126:129], v[148:151], v[184:187], v[126:129]
	v_mfma_f32_16x16x32_bf16 v[122:125], v[160:163], v[184:187], v[122:125]
	v_mfma_f32_16x16x32_bf16 v[110:113], v[148:151], v[192:195], v[110:113]
	v_mfma_f32_16x16x32_bf16 v[106:109], v[160:163], v[192:195], v[106:109]
	v_mfma_f32_16x16x32_bf16 v[94:97], v[148:151], v[200:203], v[94:97]
	v_mfma_f32_16x16x32_bf16 v[90:93], v[160:163], v[200:203], v[90:93]
	v_mfma_f32_16x16x32_bf16 v[78:81], v[148:151], v[212:215], v[78:81]
	v_mfma_f32_16x16x32_bf16 v[74:77], v[160:163], v[212:215], v[74:77]
	v_mfma_f32_16x16x32_bf16 v[126:129], v[156:159], v[188:191], v[126:129]
	v_mfma_f32_16x16x32_bf16 v[122:125], v[164:167], v[188:191], v[122:125]
	v_mfma_f32_16x16x32_bf16 v[110:113], v[156:159], v[196:199], v[110:113]
	v_mfma_f32_16x16x32_bf16 v[106:109], v[164:167], v[196:199], v[106:109]
	v_mfma_f32_16x16x32_bf16 v[94:97], v[156:159], v[208:211], v[94:97]
	v_mfma_f32_16x16x32_bf16 v[90:93], v[164:167], v[208:211], v[90:93]
	v_mfma_f32_16x16x32_bf16 v[78:81], v[156:159], v[216:219], v[78:81]
	v_mfma_f32_16x16x32_bf16 v[74:77], v[164:167], v[216:219], v[74:77]
	v_mfma_f32_16x16x32_bf16 v[118:121], v[168:171], v[184:187], v[118:121]
	v_mfma_f32_16x16x32_bf16 v[114:117], v[176:179], v[184:187], v[114:117]
	v_mfma_f32_16x16x32_bf16 v[102:105], v[168:171], v[192:195], v[102:105]
	v_mfma_f32_16x16x32_bf16 v[98:101], v[176:179], v[192:195], v[98:101]
	v_mfma_f32_16x16x32_bf16 v[86:89], v[168:171], v[200:203], v[86:89]
	v_mfma_f32_16x16x32_bf16 v[82:85], v[176:179], v[200:203], v[82:85]
	v_mfma_f32_16x16x32_bf16 v[70:73], v[168:171], v[212:215], v[70:73]
	v_mfma_f32_16x16x32_bf16 v[66:69], v[176:179], v[212:215], v[66:69]
	v_mfma_f32_16x16x32_bf16 v[118:121], v[172:175], v[188:191], v[118:121]
	v_mfma_f32_16x16x32_bf16 v[114:117], v[180:183], v[188:191], v[114:117]
	v_mfma_f32_16x16x32_bf16 v[102:105], v[172:175], v[196:199], v[102:105]
	v_mfma_f32_16x16x32_bf16 v[98:101], v[180:183], v[196:199], v[98:101]
	v_mfma_f32_16x16x32_bf16 v[86:89], v[172:175], v[208:211], v[86:89]
	v_mfma_f32_16x16x32_bf16 v[82:85], v[180:183], v[208:211], v[82:85]
	v_mfma_f32_16x16x32_bf16 v[70:73], v[172:175], v[216:219], v[70:73]
	v_mfma_f32_16x16x32_bf16 v[66:69], v[180:183], v[216:219], v[66:69]
	s_barrier
	s_add_i32 s74, s68, s30
	s_mov_b32 m0, s74
	ds_read_b128 v[184:187], v154 offset:16384
	ds_read_b128 v[188:191], v154 offset:17408
	ds_read_b128 v[192:195], v154 offset:18432
	ds_read_b128 v[196:199], v154 offset:19456
	ds_read_b128 v[200:203], v154 offset:20480
	ds_read_b128 v[208:211], v154 offset:21504
	ds_read_b128 v[212:215], v154 offset:22528
	ds_read_b128 v[216:219], v154 offset:23552
	global_load_lds_dwordx4 v132, s[46:47]
	s_add_i32 m0, s74, 0x2000
	s_add_u32 s74, s46, 0x40000
	s_addc_u32 s75, s47, 0
	s_add_i32 s76, s69, s30
	global_load_lds_dwordx4 v136, s[46:47]
	s_mov_b32 m0, s76
	s_add_u32 s100, s48, 0x80
	s_addc_u32 s101, s49, 0
	global_load_lds_dwordx4 v132, s[74:75]
	s_add_i32 m0, s76, 0x2000
	s_nop 0
	global_load_lds_dwordx4 v136, s[74:75]
	s_mov_b32 m0, s31
	s_nop 0
	global_load_lds_dwordx4 v130, s[48:49]
	s_mov_b32 m0, s50
	s_nop 0
	global_load_lds_dwordx4 v134, s[48:49]
	s_waitcnt vmcnt(8)
	s_bitcmp1_b32 s16, 0
	s_cbranch_scc1 .Lnl_646_5
	s_waitcnt lgkmcnt(0)

; #define PG8_STAGE(bufoff, gbase, voff) do { _Pragma("unroll") for (int _i = 0; _i < 2; ++_i) \
;         __builtin_amdgcn_global_load_lds((const unsigned*)((const char*)(gbase) + (voff)[_i]), (PG8_LAS unsigned*)(lds + (bufoff) + ldsw + _i * 8192), 16, 0, 0); } while (0)
; #define PG8_LDA(dst, b, h) do { _Pragma("unroll") for (int m = 0; m < 4; ++m) _Pragma("unroll") for (int k = 0; k < 2; ++k) dst[m][k] = *(const PG8_LAS bf16x8*)(lds + PG8_SA(b, h) + aoff + m * 2048 + k * 1024); } while (0)
; #define PG8_LDB(dst, b, h) do { _Pragma("unroll") for (int n = 0; n < 2; ++n) _Pragma("unroll") for (int k = 0; k < 2; ++k) dst[n][k] = *(const PG8_LAS bf16x8*)(lds + PG8_SB(b, h) + boff + n * 2048 + k * 1024); } while (0)
; #define PG8_SCHED __builtin_amdgcn_sched_barrier(0)
; template <class Epi, class Sched, bool ALIGN_EPI = false, bool SP2 = false>
; __device__ __forceinline__ void gemm_phase(PG8_LAS unsigned char* lds, const Gemm g, const Sched& S, const Epi& E) {
;     ...
;         const bool has_next = S.next(ui + 1, nxt);
;         const char* nA = has_next ? (const char*)g.A + (size_t)nxt.pm * tstep : cA; const char* nB = has_next ? (const char*)g.Bt + (size_t)nxt.pn * tstep : cB;
;         for (int t = 0; t < nt; t += 2) {
;             const bool last = (t == nt - 2);
;             const char* a1 = cA + (size_t)(t + 1) * kstep;
;             const char* a2 = last ? nA : cA + (size_t)(t + 2) * kstep; const char* b2 = last ? nB : cB + (size_t)(t + 2) * kstep;
;             const char* a3 = a2 + kstep; const char* b3 = b2 + kstep;
;             if (last && has_next) S.a_ready(nxt);
;             if constexpr (SP2) {
;             PG8_LDB(B0, 0, 0); PG8_LDB(B1, 0, 1); PG8_SCHED; PG8_LDA(At, 0, 0); PG8_STAGE(PG8_SA(1, 1), a1 + hstep, voffA);
.LBB0_739:
	s_ashr_i32 s19, s18, 31
	s_lshl_b64 s[20:21], s[18:19], 19
	s_add_u32 s20, s42, s20
	s_addc_u32 s21, s43, s21
	s_and_b64 s[22:23], s[0:1], exec
	s_cselect_b32 s19, s21, s31
	s_cselect_b32 s25, s20, s30
	s_ashr_i32 s17, s16, 31
	s_lshl_b64 s[22:23], s[16:17], 19
	s_add_u32 s22, s38, s22
	s_addc_u32 s23, s39, s23
	s_and_b64 s[44:45], s[0:1], exec
	s_cselect_b32 s17, s23, s41
	s_cselect_b32 s27, s22, s40
	s_add_u32 s30, s30, 0x40080
	s_addc_u32 s31, s31, 0
	s_add_u32 s33, s40, 0x100
	s_addc_u32 s70, s41, 0
	s_mov_b32 s71, -2
	ds_read_b128 v[156:159], v152
	ds_read_b128 v[160:163], v152 offset:1024
	ds_read_b128 v[164:167], v152 offset:2048
	ds_read_b128 v[168:171], v152 offset:3072
	ds_read_b128 v[172:175], v153
	ds_read_b128 v[176:179], v153 offset:1024
	ds_read_b128 v[180:183], v153 offset:2048
	ds_read_b128 v[184:187], v153 offset:3072
	s_add_u32 s40, s30, 0xfffc0080
	s_addc_u32 s41, s31, -1
	s_cmp_eq_u32 s71, 12
	s_cselect_b32 s45, s19, s41
	s_cselect_b32 s44, s25, s40
	s_cselect_b32 s41, s17, s70
	s_cselect_b32 s40, s27, s33
	s_add_i32 m0, s48, 0xc000
	ds_read_b128 v[188:191], v154
	ds_read_b128 v[192:195], v154 offset:1024
	ds_read_b128 v[196:199], v154 offset:2048
	ds_read_b128 v[200:203], v154 offset:3072
	ds_read_b128 v[208:211], v154 offset:4096
	ds_read_b128 v[212:215], v154 offset:5120
	ds_read_b128 v[216:219], v154 offset:6144
	ds_read_b128 v[220:223], v154 offset:7168
	global_load_lds_dwordx4 v140, s[30:31]
	s_add_i32 m0, s48, 0xe000
	s_nop 0
	global_load_lds_dwordx4 v142, s[30:31]
	s_waitcnt vmcnt(16)
	s_cmp_gt_u32 s69, 1
	s_cbranch_scc1 .Lpw_740_0
	s_waitcnt vmcnt(8)

; #define PG8_STAGE(bufoff, gbase, voff) do { _Pragma("unroll") for (int _i = 0; _i < 2; ++_i) \
;         __builtin_amdgcn_global_load_lds((const unsigned*)((const char*)(gbase) + (voff)[_i]), (PG8_LAS unsigned*)(lds + (bufoff) + ldsw + _i * 8192), 16, 0, 0); } while (0)
; #define PG8_LDA(dst, b, h) do { _Pragma("unroll") for (int m = 0; m < 4; ++m) _Pragma("unroll") for (int k = 0; k < 2; ++k) dst[m][k] = *(const PG8_LAS bf16x8*)(lds + PG8_SA(b, h) + aoff + m * 2048 + k * 1024); } while (0)
; #define PG8_LDB(dst, b, h) do { _Pragma("unroll") for (int n = 0; n < 2; ++n) _Pragma("unroll") for (int k = 0; k < 2; ++k) dst[n][k] = *(const PG8_LAS bf16x8*)(lds + PG8_SB(b, h) + boff + n * 2048 + k * 1024); } while (0)
; #define PG8_MMA(ai, bj, At, Bt) do { __builtin_amdgcn_s_setprio(1); _Pragma("unroll") for (int m = 0; m < 4; ++m) _Pragma("unroll") for (int n = 0; n < 2; ++n) _Pragma("unroll") for (int k = 0; k < 2; ++k) \
;         acc[ai][bj][m][n] = __builtin_amdgcn_mfma_f32_16x16x32_bf16(Bt[n][k], At[m][k], acc[ai][bj][m][n], 0, 0, 0); __builtin_amdgcn_s_setprio(0); } while (0)
; #define PG8_WAIT_V(n) asm volatile("s_waitcnt vmcnt(" #n ")" ::: "memory")
; #define PG8_WAIT_L(n) asm volatile("s_waitcnt lgkmcnt(" #n ")" ::: "memory")
; #define PG8_BAR __builtin_amdgcn_s_barrier()
; #define PG8_SCHED __builtin_amdgcn_sched_barrier(0)
; template <class Epi, class Sched, bool ALIGN_EPI = false, bool SP2 = false>
; __device__ __forceinline__ void gemm_phase(PG8_LAS unsigned char* lds, const Gemm g, const Sched& S, const Epi& E) {
;     ...
;             PG8_LDB(B0, 0, 0); PG8_LDB(B1, 0, 1); PG8_SCHED; PG8_LDA(At, 0, 0); PG8_STAGE(PG8_SA(1, 1), a1 + hstep, voffA);
;             PG8_WAIT_V(8); PG8_WAIT_L(0); PG8_BAR; PG8_MMA(0, 0, At, B0); PG8_MMA(0, 1, At, B1); PG8_BAR; PG8_SCHED;
;             PG8_LDA(At, 0, 1); PG8_STAGE(PG8_SB(0, 0), b2, voffB); PG8_STAGE(PG8_SB(0, 1), b2 + hstep, voffB); PG8_STAGE(PG8_SA(0, 0), a2, voffA);
.Lnl_740_0:
	s_barrier
	s_waitcnt lgkmcnt(0)
	v_mfma_f32_16x16x32_bf16 v[126:129], v[156:159], v[188:191], 0
	v_mfma_f32_16x16x32_bf16 v[122:125], v[164:167], v[188:191], 0
	v_mfma_f32_16x16x32_bf16 v[110:113], v[156:159], v[196:199], 0
	v_mfma_f32_16x16x32_bf16 v[106:109], v[164:167], v[196:199], 0
	v_mfma_f32_16x16x32_bf16 v[94:97], v[156:159], v[208:211], 0
	v_mfma_f32_16x16x32_bf16 v[90:93], v[164:167], v[208:211], 0
	v_mfma_f32_16x16x32_bf16 v[78:81], v[156:159], v[216:219], 0
	v_mfma_f32_16x16x32_bf16 v[74:77], v[164:167], v[216:219], 0
	v_mfma_f32_16x16x32_bf16 v[126:129], v[160:163], v[192:195], v[126:129]
	v_mfma_f32_16x16x32_bf16 v[122:125], v[168:171], v[192:195], v[122:125]
	v_mfma_f32_16x16x32_bf16 v[110:113], v[160:163], v[200:203], v[110:113]
	v_mfma_f32_16x16x32_bf16 v[106:109], v[168:171], v[200:203], v[106:109]
	v_mfma_f32_16x16x32_bf16 v[94:97], v[160:163], v[212:215], v[94:97]
	v_mfma_f32_16x16x32_bf16 v[90:93], v[168:171], v[212:215], v[90:93]
	v_mfma_f32_16x16x32_bf16 v[78:81], v[160:163], v[220:223], v[78:81]
	v_mfma_f32_16x16x32_bf16 v[74:77], v[168:171], v[220:223], v[74:77]
	v_mfma_f32_16x16x32_bf16 v[118:121], v[172:175], v[188:191], 0
	v_mfma_f32_16x16x32_bf16 v[114:117], v[180:183], v[188:191], 0
	v_mfma_f32_16x16x32_bf16 v[102:105], v[172:175], v[196:199], 0
	v_mfma_f32_16x16x32_bf16 v[98:101], v[180:183], v[196:199], 0
	v_mfma_f32_16x16x32_bf16 v[86:89], v[172:175], v[208:211], 0
	v_mfma_f32_16x16x32_bf16 v[82:85], v[180:183], v[208:211], 0
	v_mfma_f32_16x16x32_bf16 v[70:73], v[172:175], v[216:219], 0
	v_mfma_f32_16x16x32_bf16 v[66:69], v[180:183], v[216:219], 0
	v_mfma_f32_16x16x32_bf16 v[118:121], v[176:179], v[192:195], v[118:121]
	v_mfma_f32_16x16x32_bf16 v[114:117], v[184:187], v[192:195], v[114:117]
	v_mfma_f32_16x16x32_bf16 v[102:105], v[176:179], v[200:203], v[102:105]
	v_mfma_f32_16x16x32_bf16 v[98:101], v[184:187], v[200:203], v[98:101]
	v_mfma_f32_16x16x32_bf16 v[86:89], v[176:179], v[212:215], v[86:89]
	v_mfma_f32_16x16x32_bf16 v[82:85], v[184:187], v[212:215], v[82:85]
	v_mfma_f32_16x16x32_bf16 v[70:73], v[176:179], v[220:223], v[70:73]
	v_mfma_f32_16x16x32_bf16 v[66:69], v[184:187], v[220:223], v[66:69]
	s_barrier
	s_add_i32 s72, s66, s47
	s_mov_b32 m0, s72
	ds_read_b128 v[188:191], v154 offset:16384
	ds_read_b128 v[192:195], v154 offset:17408
	ds_read_b128 v[196:199], v154 offset:18432
	ds_read_b128 v[200:203], v154 offset:19456
	ds_read_b128 v[208:211], v154 offset:20480
	ds_read_b128 v[212:215], v154 offset:21504
	ds_read_b128 v[216:219], v154 offset:22528
	ds_read_b128 v[220:223], v154 offset:23552
	global_load_lds_dwordx4 v132, s[40:41]
	s_add_i32 m0, s72, 0x2000
	s_add_u32 s72, s40, 0x40000
	s_addc_u32 s73, s41, 0
	s_add_i32 s74, s67, s47
	global_load_lds_dwordx4 v136, s[40:41]
	s_mov_b32 m0, s74
	s_add_u32 s100, s44, 0x80
	s_addc_u32 s101, s45, 0
	global_load_lds_dwordx4 v132, s[72:73]
	s_add_i32 m0, s74, 0x2000
	s_nop 0
	global_load_lds_dwordx4 v136, s[72:73]
	s_mov_b32 m0, s48
	s_nop 0
	global_load_lds_dwordx4 v130, s[44:45]
	s_mov_b32 m0, s49
	s_nop 0
	global_load_lds_dwordx4 v134, s[44:45]
	s_waitcnt vmcnt(16)
	s_cmp_gt_u32 s69, 1
	s_cbranch_scc1 .Lpw_740_1
	s_waitcnt vmcnt(8)

; #define PG8_STAGE(bufoff, gbase, voff) do { _Pragma("unroll") for (int _i = 0; _i < 2; ++_i) \
;         __builtin_amdgcn_global_load_lds((const unsigned*)((const char*)(gbase) + (voff)[_i]), (PG8_LAS unsigned*)(lds + (bufoff) + ldsw + _i * 8192), 16, 0, 0); } while (0)
; #define PG8_LDA(dst, b, h) do { _Pragma("unroll") for (int m = 0; m < 4; ++m) _Pragma("unroll") for (int k = 0; k < 2; ++k) dst[m][k] = *(const PG8_LAS bf16x8*)(lds + PG8_SA(b, h) + aoff + m * 2048 + k * 1024); } while (0)
; template <class Epi, class Sched, bool ALIGN_EPI = false, bool SP2 = false>
; __device__ __forceinline__ void gemm_phase(PG8_LAS unsigned char* lds, const Gemm g, const Sched& S, const Epi& E) {
;     ...
;             PG8_LDA(At, 1, 1); PG8_STAGE(PG8_SB(1, 0), b3, voffB); PG8_STAGE(PG8_SB(1, 1), b3 + hstep, voffB); PG8_STAGE(PG8_SA(1, 0), a3, voffA);
.Lnl_740_2:
	s_barrier
	s_waitcnt lgkmcnt(0)
	v_mfma_f32_16x16x32_bf16 v[126:129], v[156:159], v[188:191], v[126:129]
	v_mfma_f32_16x16x32_bf16 v[122:125], v[164:167], v[188:191], v[122:125]
	v_mfma_f32_16x16x32_bf16 v[110:113], v[156:159], v[196:199], v[110:113]
	v_mfma_f32_16x16x32_bf16 v[106:109], v[164:167], v[196:199], v[106:109]
	v_mfma_f32_16x16x32_bf16 v[94:97], v[156:159], v[208:211], v[94:97]
	v_mfma_f32_16x16x32_bf16 v[90:93], v[164:167], v[208:211], v[90:93]
	v_mfma_f32_16x16x32_bf16 v[78:81], v[156:159], v[216:219], v[78:81]
	v_mfma_f32_16x16x32_bf16 v[74:77], v[164:167], v[216:219], v[74:77]
	v_mfma_f32_16x16x32_bf16 v[126:129], v[160:163], v[192:195], v[126:129]
	v_mfma_f32_16x16x32_bf16 v[122:125], v[168:171], v[192:195], v[122:125]
	v_mfma_f32_16x16x32_bf16 v[110:113], v[160:163], v[200:203], v[110:113]
	v_mfma_f32_16x16x32_bf16 v[106:109], v[168:171], v[200:203], v[106:109]
	v_mfma_f32_16x16x32_bf16 v[94:97], v[160:163], v[212:215], v[94:97]
	v_mfma_f32_16x16x32_bf16 v[90:93], v[168:171], v[212:215], v[90:93]
	v_mfma_f32_16x16x32_bf16 v[78:81], v[160:163], v[220:223], v[78:81]
	v_mfma_f32_16x16x32_bf16 v[74:77], v[168:171], v[220:223], v[74:77]
	v_mfma_f32_16x16x32_bf16 v[118:121], v[172:175], v[188:191], v[118:121]
	v_mfma_f32_16x16x32_bf16 v[114:117], v[180:183], v[188:191], v[114:117]
	v_mfma_f32_16x16x32_bf16 v[102:105], v[172:175], v[196:199], v[102:105]
	v_mfma_f32_16x16x32_bf16 v[98:101], v[180:183], v[196:199], v[98:101]
	v_mfma_f32_16x16x32_bf16 v[86:89], v[172:175], v[208:211], v[86:89]
	v_mfma_f32_16x16x32_bf16 v[82:85], v[180:183], v[208:211], v[82:85]
	v_mfma_f32_16x16x32_bf16 v[70:73], v[172:175], v[216:219], v[70:73]
	v_mfma_f32_16x16x32_bf16 v[66:69], v[180:183], v[216:219], v[66:69]
	v_mfma_f32_16x16x32_bf16 v[118:121], v[176:179], v[192:195], v[118:121]
	v_mfma_f32_16x16x32_bf16 v[114:117], v[184:187], v[192:195], v[114:117]
	v_mfma_f32_16x16x32_bf16 v[102:105], v[176:179], v[200:203], v[102:105]
	v_mfma_f32_16x16x32_bf16 v[98:101], v[184:187], v[200:203], v[98:101]
	v_mfma_f32_16x16x32_bf16 v[86:89], v[176:179], v[212:215], v[86:89]
	v_mfma_f32_16x16x32_bf16 v[82:85], v[184:187], v[212:215], v[82:85]
	v_mfma_f32_16x16x32_bf16 v[70:73], v[176:179], v[220:223], v[70:73]
	v_mfma_f32_16x16x32_bf16 v[66:69], v[184:187], v[220:223], v[66:69]
	s_barrier
	s_add_i32 s44, s72, s47
	s_mov_b32 m0, s44
	ds_read_b128 v[188:191], v154 offset:49152
	ds_read_b128 v[192:195], v154 offset:50176
	ds_read_b128 v[196:199], v154 offset:51200
	ds_read_b128 v[200:203], v154 offset:52224
	ds_read_b128 v[208:211], v154 offset:53248
	ds_read_b128 v[212:215], v154 offset:54272
	ds_read_b128 v[216:219], v154 offset:55296
	ds_read_b128 v[220:223], v154 offset:56320
	s_add_u32 s98, s40, s12
	s_addc_u32 s99, s41, s13
	global_load_lds_dwordx4 v132, s[98:99]
	s_add_i32 m0, s44, 0x2000
	s_add_u32 s40, s40, 0x40080
	s_addc_u32 s41, s41, 0
	s_add_i32 s44, s73, s47
	global_load_lds_dwordx4 v136, s[98:99]
	s_mov_b32 m0, s44
	s_nop 0
	global_load_lds_dwordx4 v132, s[40:41]
	s_add_i32 m0, s44, 0x2000
	s_nop 0
	global_load_lds_dwordx4 v136, s[40:41]
	s_mov_b32 m0, s61
	s_nop 0
	global_load_lds_dwordx4 v130, s[100:101]
	s_mov_b32 m0, s62
	s_nop 0
	global_load_lds_dwordx4 v134, s[100:101]
	s_waitcnt vmcnt(8)
	s_bitcmp1_b32 s14, 0
	s_cbranch_scc1 .Lnl_740_3
	s_waitcnt lgkmcnt(0)

; #define PG8_STAGE(bufoff, gbase, voff) do { _Pragma("unroll") for (int _i = 0; _i < 2; ++_i) \
;         __builtin_amdgcn_global_load_lds((const unsigned*)((const char*)(gbase) + (voff)[_i]), (PG8_LAS unsigned*)(lds + (bufoff) + ldsw + _i * 8192), 16, 0, 0); } while (0)
; #define PG8_LDA(dst, b, h) do { _Pragma("unroll") for (int m = 0; m < 4; ++m) _Pragma("unroll") for (int k = 0; k < 2; ++k) dst[m][k] = *(const PG8_LAS bf16x8*)(lds + PG8_SA(b, h) + aoff + m * 2048 + k * 1024); } while (0)
; #define PG8_LDB(dst, b, h) do { _Pragma("unroll") for (int n = 0; n < 2; ++n) _Pragma("unroll") for (int k = 0; k < 2; ++k) dst[n][k] = *(const PG8_LAS bf16x8*)(lds + PG8_SB(b, h) + boff + n * 2048 + k * 1024); } while (0)
; #define PG8_MMA(ai, bj, At, Bt) do { __builtin_amdgcn_s_setprio(1); _Pragma("unroll") for (int m = 0; m < 4; ++m) _Pragma("unroll") for (int n = 0; n < 2; ++n) _Pragma("unroll") for (int k = 0; k < 2; ++k) \
;         acc[ai][bj][m][n] = __builtin_amdgcn_mfma_f32_16x16x32_bf16(Bt[n][k], At[m][k], acc[ai][bj][m][n], 0, 0, 0); __builtin_amdgcn_s_setprio(0); } while (0)
; #define PG8_WAIT_V(n) asm volatile("s_waitcnt vmcnt(" #n ")" ::: "memory")
; #define PG8_WAIT_L(n) asm volatile("s_waitcnt lgkmcnt(" #n ")" ::: "memory")
; #define PG8_BAR __builtin_amdgcn_s_barrier()
; #define PG8_SCHED __builtin_amdgcn_sched_barrier(0)
; template <class Epi, class Sched, bool ALIGN_EPI = false, bool SP2 = false>
; __device__ __forceinline__ void gemm_phase(PG8_LAS unsigned char* lds, const Gemm g, const Sched& S, const Epi& E) {
;     ...
;             PG8_LDB(B0, 0, 0); PG8_LDB(B1, 0, 1); PG8_SCHED; PG8_LDA(At, 0, 0); PG8_STAGE(PG8_SA(1, 1), a1 + hstep, voffA);
;             PG8_WAIT_V(8); PG8_WAIT_L(0); PG8_BAR; PG8_MMA(0, 0, At, B0); PG8_MMA(0, 1, At, B1); PG8_BAR; PG8_SCHED;
;             PG8_LDA(At, 0, 1); PG8_STAGE(PG8_SB(0, 0), b2, voffB); PG8_STAGE(PG8_SB(0, 1), b2 + hstep, voffB); PG8_STAGE(PG8_SA(0, 0), a2, voffA);
.LBB0_740:
	ds_read_b128 v[156:159], v152
	ds_read_b128 v[160:163], v152 offset:1024
	ds_read_b128 v[164:167], v152 offset:2048
	ds_read_b128 v[168:171], v152 offset:3072
	ds_read_b128 v[172:175], v153
	ds_read_b128 v[176:179], v153 offset:1024
	ds_read_b128 v[180:183], v153 offset:2048
	ds_read_b128 v[184:187], v153 offset:3072
	s_add_u32 s40, s30, 0xfffc0080
	s_addc_u32 s41, s31, -1
	s_cmp_eq_u32 s71, 12
	s_cselect_b32 s45, s19, s41
	s_cselect_b32 s44, s25, s40
	s_cselect_b32 s41, s17, s70
	s_cselect_b32 s40, s27, s33
	s_add_i32 m0, s48, 0xc000
	ds_read_b128 v[188:191], v154
	ds_read_b128 v[192:195], v154 offset:1024
	ds_read_b128 v[196:199], v154 offset:2048
	ds_read_b128 v[200:203], v154 offset:3072
	ds_read_b128 v[208:211], v154 offset:4096
	ds_read_b128 v[212:215], v154 offset:5120
	ds_read_b128 v[216:219], v154 offset:6144
	ds_read_b128 v[220:223], v154 offset:7168
	global_load_lds_dwordx4 v140, s[30:31]
	s_add_i32 m0, s48, 0xe000
	s_nop 0
	global_load_lds_dwordx4 v142, s[30:31]
	s_waitcnt vmcnt(8)
	s_bitcmp1_b32 s14, 0
	s_cbranch_scc1 .Lnl_740_4
	s_waitcnt lgkmcnt(0)
.Lnl_740_4:
	s_barrier
	s_waitcnt lgkmcnt(0)
	v_mfma_f32_16x16x32_bf16 v[126:129], v[156:159], v[188:191], v[126:129]
	v_mfma_f32_16x16x32_bf16 v[122:125], v[164:167], v[188:191], v[122:125]
	v_mfma_f32_16x16x32_bf16 v[110:113], v[156:159], v[196:199], v[110:113]
	v_mfma_f32_16x16x32_bf16 v[106:109], v[164:167], v[196:199], v[106:109]
	v_mfma_f32_16x16x32_bf16 v[94:97], v[156:159], v[208:211], v[94:97]
	v_mfma_f32_16x16x32_bf16 v[90:93], v[164:167], v[208:211], v[90:93]
	v_mfma_f32_16x16x32_bf16 v[78:81], v[156:159], v[216:219], v[78:81]
	v_mfma_f32_16x16x32_bf16 v[74:77], v[164:167], v[216:219], v[74:77]
	v_mfma_f32_16x16x32_bf16 v[126:129], v[160:163], v[192:195], v[126:129]
	v_mfma_f32_16x16x32_bf16 v[122:125], v[168:171], v[192:195], v[122:125]
	v_mfma_f32_16x16x32_bf16 v[110:113], v[160:163], v[200:203], v[110:113]
	v_mfma_f32_16x16x32_bf16 v[106:109], v[168:171], v[200:203], v[106:109]
	v_mfma_f32_16x16x32_bf16 v[94:97], v[160:163], v[212:215], v[94:97]
	v_mfma_f32_16x16x32_bf16 v[90:93], v[168:171], v[212:215], v[90:93]
	v_mfma_f32_16x16x32_bf16 v[78:81], v[160:163], v[220:223], v[78:81]
	v_mfma_f32_16x16x32_bf16 v[74:77], v[168:171], v[220:223], v[74:77]
	v_mfma_f32_16x16x32_bf16 v[118:121], v[172:175], v[188:191], v[118:121]
	v_mfma_f32_16x16x32_bf16 v[114:117], v[180:183], v[188:191], v[114:117]
	v_mfma_f32_16x16x32_bf16 v[102:105], v[172:175], v[196:199], v[102:105]
	v_mfma_f32_16x16x32_bf16 v[98:101], v[180:183], v[196:199], v[98:101]
	v_mfma_f32_16x16x32_bf16 v[86:89], v[172:175], v[208:211], v[86:89]
	v_mfma_f32_16x16x32_bf16 v[82:85], v[180:183], v[208:211], v[82:85]
	v_mfma_f32_16x16x32_bf16 v[70:73], v[172:175], v[216:219], v[70:73]
	v_mfma_f32_16x16x32_bf16 v[66:69], v[180:183], v[216:219], v[66:69]
	v_mfma_f32_16x16x32_bf16 v[118:121], v[176:179], v[192:195], v[118:121]
	v_mfma_f32_16x16x32_bf16 v[114:117], v[184:187], v[192:195], v[114:117]
	v_mfma_f32_16x16x32_bf16 v[102:105], v[176:179], v[200:203], v[102:105]
	v_mfma_f32_16x16x32_bf16 v[98:101], v[184:187], v[200:203], v[98:101]
	v_mfma_f32_16x16x32_bf16 v[86:89], v[176:179], v[212:215], v[86:89]
	v_mfma_f32_16x16x32_bf16 v[82:85], v[184:187], v[212:215], v[82:85]
	v_mfma_f32_16x16x32_bf16 v[70:73], v[176:179], v[220:223], v[70:73]
	v_mfma_f32_16x16x32_bf16 v[66:69], v[184:187], v[220:223], v[66:69]
	s_barrier
	s_add_i32 s72, s66, s47
	s_mov_b32 m0, s72
	ds_read_b128 v[188:191], v154 offset:16384
	ds_read_b128 v[192:195], v154 offset:17408
	ds_read_b128 v[196:199], v154 offset:18432
	ds_read_b128 v[200:203], v154 offset:19456
	ds_read_b128 v[208:211], v154 offset:20480
	ds_read_b128 v[212:215], v154 offset:21504
	ds_read_b128 v[216:219], v154 offset:22528
	ds_read_b128 v[220:223], v154 offset:23552
	global_load_lds_dwordx4 v132, s[40:41]
	s_add_i32 m0, s72, 0x2000
	s_add_u32 s72, s40, 0x40000
	s_addc_u32 s73, s41, 0
	s_add_i32 s74, s67, s47
	global_load_lds_dwordx4 v136, s[40:41]
	s_mov_b32 m0, s74
	s_add_u32 s100, s44, 0x80
	s_addc_u32 s101, s45, 0
	global_load_lds_dwordx4 v132, s[72:73]
	s_add_i32 m0, s74, 0x2000
	s_nop 0
	global_load_lds_dwordx4 v136, s[72:73]
	s_mov_b32 m0, s48
	s_nop 0
	global_load_lds_dwordx4 v130, s[44:45]
	s_mov_b32 m0, s49
	s_nop 0
	global_load_lds_dwordx4 v134, s[44:45]
	s_waitcnt vmcnt(8)
	s_bitcmp1_b32 s14, 0
	s_cbranch_scc1 .Lnl_740_5
	s_waitcnt lgkmcnt(0)

; #define PG8_STAGE(bufoff, gbase, voff) do { _Pragma("unroll") for (int _i = 0; _i < 2; ++_i) \
;         __builtin_amdgcn_global_load_lds((const unsigned*)((const char*)(gbase) + (voff)[_i]), (PG8_LAS unsigned*)(lds + (bufoff) + ldsw + _i * 8192), 16, 0, 0); } while (0)
; #define PG8_LDA(dst, b, h) do { _Pragma("unroll") for (int m = 0; m < 4; ++m) _Pragma("unroll") for (int k = 0; k < 2; ++k) dst[m][k] = *(const PG8_LAS bf16x8*)(lds + PG8_SA(b, h) + aoff + m * 2048 + k * 1024); } while (0)
; #define PG8_LDB(dst, b, h) do { _Pragma("unroll") for (int n = 0; n < 2; ++n) _Pragma("unroll") for (int k = 0; k < 2; ++k) dst[n][k] = *(const PG8_LAS bf16x8*)(lds + PG8_SB(b, h) + boff + n * 2048 + k * 1024); } while (0)
; #define PG8_MMA(ai, bj, At, Bt) do { __builtin_amdgcn_s_setprio(1); _Pragma("unroll") for (int m = 0; m < 4; ++m) _Pragma("unroll") for (int n = 0; n < 2; ++n) _Pragma("unroll") for (int k = 0; k < 2; ++k) \
;         acc[ai][bj][m][n] = __builtin_amdgcn_mfma_f32_16x16x32_bf16(Bt[n][k], At[m][k], acc[ai][bj][m][n], 0, 0, 0); __builtin_amdgcn_s_setprio(0); } while (0)
; #define PG8_WAIT_V(n) asm volatile("s_waitcnt vmcnt(" #n ")" ::: "memory")
; #define PG8_WAIT_L(n) asm volatile("s_waitcnt lgkmcnt(" #n ")" ::: "memory")
; #define PG8_BAR __builtin_amdgcn_s_barrier()
; #define PG8_SCHED __builtin_amdgcn_sched_barrier(0)
; template <class Epi, class Sched, bool ALIGN_EPI = false, bool SP2 = false>
; __device__ __forceinline__ void gemm_phase(PG8_LAS unsigned char* lds, const Gemm g, const Sched& S, const Epi& E) {
;     ...
;         for (int t = 0; t < nt; t += 2) {
;             const bool last = (t == nt - 2);
;             const char* a1 = cA + (size_t)(t + 1) * kstep;
;             const char* a2 = last ? nA : cA + (size_t)(t + 2) * kstep; const char* b2 = last ? nB : cB + (size_t)(t + 2) * kstep;
;             const char* a3 = a2 + kstep; const char* b3 = b2 + kstep;
;             if (last && has_next) S.a_ready(nxt);
;             if constexpr (SP2) {
;             PG8_LDB(B0, 0, 0); PG8_LDB(B1, 0, 1); PG8_SCHED; PG8_LDA(At, 0, 0); PG8_STAGE(PG8_SA(1, 1), a1 + hstep, voffA);
;             PG8_WAIT_V(8); PG8_WAIT_L(0); PG8_BAR; PG8_MMA(0, 0, At, B0); PG8_MMA(0, 1, At, B1); PG8_BAR; PG8_SCHED;
;             PG8_LDA(At, 0, 1); PG8_STAGE(PG8_SB(0, 0), b2, voffB); PG8_STAGE(PG8_SB(0, 1), b2 + hstep, voffB); PG8_STAGE(PG8_SA(0, 0), a2, voffA);
.LBB0_860:
	s_add_u32 s24, s24, 0xb0080
	s_addc_u32 s25, s25, 0
	s_add_u32 s51, s26, 0x100
	s_addc_u32 s52, s27, 0
	s_mov_b32 s53, -2
	ds_read_b128 v[146:149], v153
	ds_read_b128 v[156:159], v153 offset:1024
	ds_read_b128 v[160:163], v153 offset:2048
	ds_read_b128 v[164:167], v153 offset:3072
	ds_read_b128 v[168:171], v154
	ds_read_b128 v[172:175], v154 offset:1024
	ds_read_b128 v[176:179], v154 offset:2048
	ds_read_b128 v[180:183], v154 offset:3072
	s_add_u32 s26, s24, 0xfff50080
	s_addc_u32 s27, s25, -1
	s_cmp_eq_u32 s53, 40
	s_cselect_b32 s29, s5, s27
	s_cselect_b32 s28, s4, s26
	s_cselect_b32 s27, s23, s52
	s_cselect_b32 s26, s22, s51
	s_add_i32 m0, s33, 0xc000
	ds_read_b128 v[184:187], v155
	ds_read_b128 v[188:191], v155 offset:1024
	ds_read_b128 v[192:195], v155 offset:2048
	ds_read_b128 v[196:199], v155 offset:3072
	ds_read_b128 v[200:203], v155 offset:4096
	ds_read_b128 v[204:207], v155 offset:5120
	ds_read_b128 v[208:211], v155 offset:6144
	ds_read_b128 v[212:215], v155 offset:7168
	global_load_lds_dwordx4 v138, s[24:25]
	s_add_i32 m0, s33, 0xe000
	s_nop 0
	global_load_lds_dwordx4 v140, s[24:25]
	s_waitcnt vmcnt(8)
	s_bitcmp1_b32 s12, 0
	s_cbranch_scc1 .Lnl_861_0
	s_waitcnt lgkmcnt(0)
.Lnl_861_0:
	s_barrier
	s_waitcnt lgkmcnt(0)
	v_mfma_f32_16x16x32_bf16 v[124:127], v[146:149], v[184:187], 0
	v_mfma_f32_16x16x32_bf16 v[120:123], v[160:163], v[184:187], 0
	v_mfma_f32_16x16x32_bf16 v[108:111], v[146:149], v[192:195], 0
	v_mfma_f32_16x16x32_bf16 v[104:107], v[160:163], v[192:195], 0
	v_mfma_f32_16x16x32_bf16 v[92:95], v[146:149], v[200:203], 0
	v_mfma_f32_16x16x32_bf16 v[88:91], v[160:163], v[200:203], 0
	v_mfma_f32_16x16x32_bf16 v[76:79], v[146:149], v[208:211], 0
	v_mfma_f32_16x16x32_bf16 v[72:75], v[160:163], v[208:211], 0
	v_mfma_f32_16x16x32_bf16 v[124:127], v[156:159], v[188:191], v[124:127]
	v_mfma_f32_16x16x32_bf16 v[120:123], v[164:167], v[188:191], v[120:123]
	v_mfma_f32_16x16x32_bf16 v[108:111], v[156:159], v[196:199], v[108:111]
	v_mfma_f32_16x16x32_bf16 v[104:107], v[164:167], v[196:199], v[104:107]
	v_mfma_f32_16x16x32_bf16 v[92:95], v[156:159], v[204:207], v[92:95]
	v_mfma_f32_16x16x32_bf16 v[88:91], v[164:167], v[204:207], v[88:91]
	v_mfma_f32_16x16x32_bf16 v[76:79], v[156:159], v[212:215], v[76:79]
	v_mfma_f32_16x16x32_bf16 v[72:75], v[164:167], v[212:215], v[72:75]
	v_mfma_f32_16x16x32_bf16 v[116:119], v[168:171], v[184:187], 0
	v_mfma_f32_16x16x32_bf16 v[112:115], v[176:179], v[184:187], 0
	v_mfma_f32_16x16x32_bf16 v[100:103], v[168:171], v[192:195], 0
	v_mfma_f32_16x16x32_bf16 v[96:99], v[176:179], v[192:195], 0
	v_mfma_f32_16x16x32_bf16 v[84:87], v[168:171], v[200:203], 0
	v_mfma_f32_16x16x32_bf16 v[80:83], v[176:179], v[200:203], 0
	v_mfma_f32_16x16x32_bf16 v[68:71], v[168:171], v[208:211], 0
	v_mfma_f32_16x16x32_bf16 v[64:67], v[176:179], v[208:211], 0
	v_mfma_f32_16x16x32_bf16 v[116:119], v[172:175], v[188:191], v[116:119]
	v_mfma_f32_16x16x32_bf16 v[112:115], v[180:183], v[188:191], v[112:115]
	v_mfma_f32_16x16x32_bf16 v[100:103], v[172:175], v[196:199], v[100:103]
	v_mfma_f32_16x16x32_bf16 v[96:99], v[180:183], v[196:199], v[96:99]
	v_mfma_f32_16x16x32_bf16 v[84:87], v[172:175], v[204:207], v[84:87]
	v_mfma_f32_16x16x32_bf16 v[80:83], v[180:183], v[204:207], v[80:83]
	v_mfma_f32_16x16x32_bf16 v[68:71], v[172:175], v[212:215], v[68:71]
	v_mfma_f32_16x16x32_bf16 v[64:67], v[180:183], v[212:215], v[64:67]
	s_barrier
	s_add_i32 s56, s45, s31
	s_mov_b32 m0, s56
	ds_read_b128 v[184:187], v155 offset:16384
	ds_read_b128 v[188:191], v155 offset:17408
	ds_read_b128 v[192:195], v155 offset:18432
	ds_read_b128 v[196:199], v155 offset:19456
	ds_read_b128 v[200:203], v155 offset:20480
	ds_read_b128 v[204:207], v155 offset:21504
	ds_read_b128 v[208:211], v155 offset:22528
	ds_read_b128 v[212:215], v155 offset:23552
	global_load_lds_dwordx4 v130, s[26:27]
	s_add_i32 m0, s56, 0x2000
	s_add_u32 s56, s26, 0xb0000
	s_addc_u32 s57, s27, 0
	s_add_i32 s58, s46, s31
	global_load_lds_dwordx4 v134, s[26:27]
	s_mov_b32 m0, s58
	s_add_u32 s100, s28, 0x80
	s_addc_u32 s101, s29, 0
	global_load_lds_dwordx4 v130, s[56:57]
	s_add_i32 m0, s58, 0x2000
	s_nop 0
	global_load_lds_dwordx4 v134, s[56:57]
	s_mov_b32 m0, s33
	s_nop 0
	global_load_lds_dwordx4 v128, s[28:29]
	s_mov_b32 m0, s36
	s_nop 0
	global_load_lds_dwordx4 v132, s[28:29]
	s_waitcnt vmcnt(8)
	s_bitcmp1_b32 s12, 0
	s_cbranch_scc1 .Lnl_861_1
	s_waitcnt lgkmcnt(0)

; #define PG8_STAGE(bufoff, gbase, voff) do { _Pragma("unroll") for (int _i = 0; _i < 2; ++_i) \
;         __builtin_amdgcn_global_load_lds((const unsigned*)((const char*)(gbase) + (voff)[_i]), (PG8_LAS unsigned*)(lds + (bufoff) + ldsw + _i * 8192), 16, 0, 0); } while (0)
; #define PG8_LDA(dst, b, h) do { _Pragma("unroll") for (int m = 0; m < 4; ++m) _Pragma("unroll") for (int k = 0; k < 2; ++k) dst[m][k] = *(const PG8_LAS bf16x8*)(lds + PG8_SA(b, h) + aoff + m * 2048 + k * 1024); } while (0)
; template <class Epi, class Sched, bool ALIGN_EPI = false, bool SP2 = false>
; __device__ __forceinline__ void gemm_phase(PG8_LAS unsigned char* lds, const Gemm g, const Sched& S, const Epi& E) {
;     ...
;             PG8_LDA(At, 1, 1); PG8_STAGE(PG8_SB(1, 0), b3, voffB); PG8_STAGE(PG8_SB(1, 1), b3 + hstep, voffB); PG8_STAGE(PG8_SA(1, 0), a3, voffA);
.Lnl_861_2:
	s_barrier
	s_waitcnt lgkmcnt(0)
	v_mfma_f32_16x16x32_bf16 v[124:127], v[146:149], v[184:187], v[124:127]
	v_mfma_f32_16x16x32_bf16 v[120:123], v[160:163], v[184:187], v[120:123]
	v_mfma_f32_16x16x32_bf16 v[108:111], v[146:149], v[192:195], v[108:111]
	v_mfma_f32_16x16x32_bf16 v[104:107], v[160:163], v[192:195], v[104:107]
	v_mfma_f32_16x16x32_bf16 v[92:95], v[146:149], v[200:203], v[92:95]
	v_mfma_f32_16x16x32_bf16 v[88:91], v[160:163], v[200:203], v[88:91]
	v_mfma_f32_16x16x32_bf16 v[76:79], v[146:149], v[208:211], v[76:79]
	v_mfma_f32_16x16x32_bf16 v[72:75], v[160:163], v[208:211], v[72:75]
	v_mfma_f32_16x16x32_bf16 v[124:127], v[156:159], v[188:191], v[124:127]
	v_mfma_f32_16x16x32_bf16 v[120:123], v[164:167], v[188:191], v[120:123]
	v_mfma_f32_16x16x32_bf16 v[108:111], v[156:159], v[196:199], v[108:111]
	v_mfma_f32_16x16x32_bf16 v[104:107], v[164:167], v[196:199], v[104:107]
	v_mfma_f32_16x16x32_bf16 v[92:95], v[156:159], v[204:207], v[92:95]
	v_mfma_f32_16x16x32_bf16 v[88:91], v[164:167], v[204:207], v[88:91]
	v_mfma_f32_16x16x32_bf16 v[76:79], v[156:159], v[212:215], v[76:79]
	v_mfma_f32_16x16x32_bf16 v[72:75], v[164:167], v[212:215], v[72:75]
	v_mfma_f32_16x16x32_bf16 v[116:119], v[168:171], v[184:187], v[116:119]
	v_mfma_f32_16x16x32_bf16 v[112:115], v[176:179], v[184:187], v[112:115]
	v_mfma_f32_16x16x32_bf16 v[100:103], v[168:171], v[192:195], v[100:103]
	v_mfma_f32_16x16x32_bf16 v[96:99], v[176:179], v[192:195], v[96:99]
	v_mfma_f32_16x16x32_bf16 v[84:87], v[168:171], v[200:203], v[84:87]
	v_mfma_f32_16x16x32_bf16 v[80:83], v[176:179], v[200:203], v[80:83]
	v_mfma_f32_16x16x32_bf16 v[68:71], v[168:171], v[208:211], v[68:71]
	v_mfma_f32_16x16x32_bf16 v[64:67], v[176:179], v[208:211], v[64:67]
	v_mfma_f32_16x16x32_bf16 v[116:119], v[172:175], v[188:191], v[116:119]
	v_mfma_f32_16x16x32_bf16 v[112:115], v[180:183], v[188:191], v[112:115]
	v_mfma_f32_16x16x32_bf16 v[100:103], v[172:175], v[196:199], v[100:103]
	v_mfma_f32_16x16x32_bf16 v[96:99], v[180:183], v[196:199], v[96:99]
	v_mfma_f32_16x16x32_bf16 v[84:87], v[172:175], v[204:207], v[84:87]
	v_mfma_f32_16x16x32_bf16 v[80:83], v[180:183], v[204:207], v[80:83]
	v_mfma_f32_16x16x32_bf16 v[68:71], v[172:175], v[212:215], v[68:71]
	v_mfma_f32_16x16x32_bf16 v[64:67], v[180:183], v[212:215], v[64:67]
	s_barrier
	s_add_i32 s28, s56, s31
	s_mov_b32 m0, s28
	ds_read_b128 v[184:187], v155 offset:49152
	ds_read_b128 v[188:191], v155 offset:50176
	ds_read_b128 v[192:195], v155 offset:51200
	ds_read_b128 v[196:199], v155 offset:52224
	ds_read_b128 v[200:203], v155 offset:53248
	ds_read_b128 v[204:207], v155 offset:54272
	ds_read_b128 v[208:211], v155 offset:55296
	ds_read_b128 v[212:215], v155 offset:56320
	s_add_u32 s98, s26, s10
	s_addc_u32 s99, s27, s11
	global_load_lds_dwordx4 v130, s[98:99]
	s_add_i32 m0, s28, 0x2000
	s_add_u32 s26, s26, 0xb0080
	s_addc_u32 s27, s27, 0
	s_add_i32 s28, s57, s31
	global_load_lds_dwordx4 v134, s[98:99]
	s_mov_b32 m0, s28
	s_nop 0
	global_load_lds_dwordx4 v130, s[26:27]
	s_add_i32 m0, s28, 0x2000
	s_nop 0
	global_load_lds_dwordx4 v134, s[26:27]
	s_mov_b32 m0, s40
	s_nop 0
	global_load_lds_dwordx4 v128, s[100:101]
	s_mov_b32 m0, s41
	s_nop 0
	global_load_lds_dwordx4 v132, s[100:101]
	s_waitcnt vmcnt(8)
	s_bitcmp1_b32 s12, 0
	s_cbranch_scc1 .Lnl_861_3
	s_waitcnt lgkmcnt(0)

; #define PG8_STAGE(bufoff, gbase, voff) do { _Pragma("unroll") for (int _i = 0; _i < 2; ++_i) \
;         __builtin_amdgcn_global_load_lds((const unsigned*)((const char*)(gbase) + (voff)[_i]), (PG8_LAS unsigned*)(lds + (bufoff) + ldsw + _i * 8192), 16, 0, 0); } while (0)
; #define PG8_LDA(dst, b, h) do { _Pragma("unroll") for (int m = 0; m < 4; ++m) _Pragma("unroll") for (int k = 0; k < 2; ++k) dst[m][k] = *(const PG8_LAS bf16x8*)(lds + PG8_SA(b, h) + aoff + m * 2048 + k * 1024); } while (0)
; #define PG8_LDB(dst, b, h) do { _Pragma("unroll") for (int n = 0; n < 2; ++n) _Pragma("unroll") for (int k = 0; k < 2; ++k) dst[n][k] = *(const PG8_LAS bf16x8*)(lds + PG8_SB(b, h) + boff + n * 2048 + k * 1024); } while (0)
; #define PG8_MMA(ai, bj, At, Bt) do { __builtin_amdgcn_s_setprio(1); _Pragma("unroll") for (int m = 0; m < 4; ++m) _Pragma("unroll") for (int n = 0; n < 2; ++n) _Pragma("unroll") for (int k = 0; k < 2; ++k) \
;         acc[ai][bj][m][n] = __builtin_amdgcn_mfma_f32_16x16x32_bf16(Bt[n][k], At[m][k], acc[ai][bj][m][n], 0, 0, 0); __builtin_amdgcn_s_setprio(0); } while (0)
; #define PG8_WAIT_V(n) asm volatile("s_waitcnt vmcnt(" #n ")" ::: "memory")
; #define PG8_WAIT_L(n) asm volatile("s_waitcnt lgkmcnt(" #n ")" ::: "memory")
; #define PG8_BAR __builtin_amdgcn_s_barrier()
; #define PG8_SCHED __builtin_amdgcn_sched_barrier(0)
; template <class Epi, class Sched, bool ALIGN_EPI = false, bool SP2 = false>
; __device__ __forceinline__ void gemm_phase(PG8_LAS unsigned char* lds, const Gemm g, const Sched& S, const Epi& E) {
;     ...
;             PG8_LDB(B0, 0, 0); PG8_LDB(B1, 0, 1); PG8_SCHED; PG8_LDA(At, 0, 0); PG8_STAGE(PG8_SA(1, 1), a1 + hstep, voffA);
;             PG8_WAIT_V(8); PG8_WAIT_L(0); PG8_BAR; PG8_MMA(0, 0, At, B0); PG8_MMA(0, 1, At, B1); PG8_BAR; PG8_SCHED;
;             PG8_LDA(At, 0, 1); PG8_STAGE(PG8_SB(0, 0), b2, voffB); PG8_STAGE(PG8_SB(0, 1), b2 + hstep, voffB); PG8_STAGE(PG8_SA(0, 0), a2, voffA);
.LBB0_861:
	ds_read_b128 v[146:149], v153
	ds_read_b128 v[156:159], v153 offset:1024
	ds_read_b128 v[160:163], v153 offset:2048
	ds_read_b128 v[164:167], v153 offset:3072
	ds_read_b128 v[168:171], v154
	ds_read_b128 v[172:175], v154 offset:1024
	ds_read_b128 v[176:179], v154 offset:2048
	ds_read_b128 v[180:183], v154 offset:3072
	s_add_u32 s26, s24, 0xfff50080
	s_addc_u32 s27, s25, -1
	s_cmp_eq_u32 s53, 40
	s_cselect_b32 s29, s5, s27
	s_cselect_b32 s28, s4, s26
	s_cselect_b32 s27, s23, s52
	s_cselect_b32 s26, s22, s51
	s_add_i32 m0, s33, 0xc000
	ds_read_b128 v[184:187], v155
	ds_read_b128 v[188:191], v155 offset:1024
	ds_read_b128 v[192:195], v155 offset:2048
	ds_read_b128 v[196:199], v155 offset:3072
	ds_read_b128 v[200:203], v155 offset:4096
	ds_read_b128 v[204:207], v155 offset:5120
	ds_read_b128 v[208:211], v155 offset:6144
	ds_read_b128 v[212:215], v155 offset:7168
	global_load_lds_dwordx4 v138, s[24:25]
	s_add_i32 m0, s33, 0xe000
	s_nop 0
	global_load_lds_dwordx4 v140, s[24:25]
	s_waitcnt vmcnt(8)
	s_bitcmp1_b32 s12, 0
	s_cbranch_scc1 .Lnl_861_4
	s_waitcnt lgkmcnt(0)
.Lnl_861_4:
	s_barrier
	s_waitcnt lgkmcnt(0)
	v_mfma_f32_16x16x32_bf16 v[124:127], v[146:149], v[184:187], v[124:127]
	v_mfma_f32_16x16x32_bf16 v[120:123], v[160:163], v[184:187], v[120:123]
	v_mfma_f32_16x16x32_bf16 v[108:111], v[146:149], v[192:195], v[108:111]
	v_mfma_f32_16x16x32_bf16 v[104:107], v[160:163], v[192:195], v[104:107]
	v_mfma_f32_16x16x32_bf16 v[92:95], v[146:149], v[200:203], v[92:95]
	v_mfma_f32_16x16x32_bf16 v[88:91], v[160:163], v[200:203], v[88:91]
	v_mfma_f32_16x16x32_bf16 v[76:79], v[146:149], v[208:211], v[76:79]
	v_mfma_f32_16x16x32_bf16 v[72:75], v[160:163], v[208:211], v[72:75]
	v_mfma_f32_16x16x32_bf16 v[124:127], v[156:159], v[188:191], v[124:127]
	v_mfma_f32_16x16x32_bf16 v[120:123], v[164:167], v[188:191], v[120:123]
	v_mfma_f32_16x16x32_bf16 v[108:111], v[156:159], v[196:199], v[108:111]
	v_mfma_f32_16x16x32_bf16 v[104:107], v[164:167], v[196:199], v[104:107]
	v_mfma_f32_16x16x32_bf16 v[92:95], v[156:159], v[204:207], v[92:95]
	v_mfma_f32_16x16x32_bf16 v[88:91], v[164:167], v[204:207], v[88:91]
	v_mfma_f32_16x16x32_bf16 v[76:79], v[156:159], v[212:215], v[76:79]
	v_mfma_f32_16x16x32_bf16 v[72:75], v[164:167], v[212:215], v[72:75]
	v_mfma_f32_16x16x32_bf16 v[116:119], v[168:171], v[184:187], v[116:119]
	v_mfma_f32_16x16x32_bf16 v[112:115], v[176:179], v[184:187], v[112:115]
	v_mfma_f32_16x16x32_bf16 v[100:103], v[168:171], v[192:195], v[100:103]
	v_mfma_f32_16x16x32_bf16 v[96:99], v[176:179], v[192:195], v[96:99]
	v_mfma_f32_16x16x32_bf16 v[84:87], v[168:171], v[200:203], v[84:87]
	v_mfma_f32_16x16x32_bf16 v[80:83], v[176:179], v[200:203], v[80:83]
	v_mfma_f32_16x16x32_bf16 v[68:71], v[168:171], v[208:211], v[68:71]
	v_mfma_f32_16x16x32_bf16 v[64:67], v[176:179], v[208:211], v[64:67]
	v_mfma_f32_16x16x32_bf16 v[116:119], v[172:175], v[188:191], v[116:119]
	v_mfma_f32_16x16x32_bf16 v[112:115], v[180:183], v[188:191], v[112:115]
	v_mfma_f32_16x16x32_bf16 v[100:103], v[172:175], v[196:199], v[100:103]
	v_mfma_f32_16x16x32_bf16 v[96:99], v[180:183], v[196:199], v[96:99]
	v_mfma_f32_16x16x32_bf16 v[84:87], v[172:175], v[204:207], v[84:87]
	v_mfma_f32_16x16x32_bf16 v[80:83], v[180:183], v[204:207], v[80:83]
	v_mfma_f32_16x16x32_bf16 v[68:71], v[172:175], v[212:215], v[68:71]
	v_mfma_f32_16x16x32_bf16 v[64:67], v[180:183], v[212:215], v[64:67]
	s_barrier
	s_add_i32 s56, s45, s31
	s_mov_b32 m0, s56
	ds_read_b128 v[184:187], v155 offset:16384
	ds_read_b128 v[188:191], v155 offset:17408
	ds_read_b128 v[192:195], v155 offset:18432
	ds_read_b128 v[196:199], v155 offset:19456
	ds_read_b128 v[200:203], v155 offset:20480
	ds_read_b128 v[204:207], v155 offset:21504
	ds_read_b128 v[208:211], v155 offset:22528
	ds_read_b128 v[212:215], v155 offset:23552
	global_load_lds_dwordx4 v130, s[26:27]
	s_add_i32 m0, s56, 0x2000
	s_add_u32 s56, s26, 0xb0000
	s_addc_u32 s57, s27, 0
	s_add_i32 s58, s46, s31
	global_load_lds_dwordx4 v134, s[26:27]
	s_mov_b32 m0, s58
	s_add_u32 s100, s28, 0x80
	s_addc_u32 s101, s29, 0
	global_load_lds_dwordx4 v130, s[56:57]
	s_add_i32 m0, s58, 0x2000
	s_nop 0
	global_load_lds_dwordx4 v134, s[56:57]
	s_mov_b32 m0, s33
	s_nop 0
	global_load_lds_dwordx4 v128, s[28:29]
	s_mov_b32 m0, s36
	s_nop 0
	global_load_lds_dwordx4 v132, s[28:29]
	s_waitcnt vmcnt(8)
	s_bitcmp1_b32 s12, 0
	s_cbranch_scc1 .Lnl_861_5
	s_waitcnt lgkmcnt(0)
